# k43 + softmax epilogue row-factor loads as an up-front pipelined pre-pass + attention: redundant canonicalising v_max and +0 adds removed, first QK MFMA issued ahead of the leading VALU block
# baseline (speedup 1.0000x reference)
.LBB0_1292:
	s_mov_b64 s[2:3], s[20:21]
	s_mov_b32 s4, 0x22174
	s_add_u32 s48, s2, 0x9800000
	s_addc_u32 s49, s3, 0
	s_add_i32 s4, s4, 0
	v_mov_b32_e32 v0, s4
	ds_read_b32 v0, v0
	s_mov_b32 s5, s33
	s_mov_b32 s6, -1
	v_mov_b64_e32 v[2:3], s[48:49]
	s_waitcnt lgkmcnt(0)
	v_readfirstlane_b32 s37, v0
	s_lshl_b32 s4, s37, 5
	s_and_b32 s42, s4, 0xe0
	s_ashr_i32 s41, s37, 3
	v_mbcnt_lo_u32_b32 v0, s6, 0
	s_add_i32 s42, s42, s41
	v_mbcnt_hi_u32_b32 v0, s6, v0
	s_ashr_i32 s4, s42, 5
	v_lshl_or_b32 v6, s5, 6, v0
	s_lshl_b32 s8, s4, 3
	v_ashrrev_i32_e32 v8, 6, v6
	s_bfe_u32 s12, s37, 0x30005
	v_add_u32_e32 v0, s8, v8
	v_and_b32_e32 v7, 63, v6
	v_mad_i64_i32 v[2:3], s[6:7], v0, s73, v[2:3]
	s_lshl_b32 s26, s12, 10
	v_lshl_add_u64 v[2:3], v[2:3], 0, s[26:27]
	v_lshlrev_b32_e32 v0, 4, v7
	v_lshl_add_u64 v[2:3], v[2:3], 0, v[0:1]
	s_mov_b32 s5, 0x140000
	v_add_co_u32_e32 v2, vcc, s5, v2
	v_lshlrev_b32_e32 v9, 2, v7
	s_nop 0
	v_addc_co_u32_e32 v3, vcc, 0, v3, vcc
	global_load_dwordx4 v[2:5], v[2:3], off sc1
	v_add_u32_e32 v0, -4, v9
	v_cmp_eq_u32_e32 vcc, 0, v7
	v_add_u32_e32 v10, -8, v9
	s_waitcnt vmcnt(0)
	v_add_f32_e32 v3, v2, v3
	v_add_f32_e32 v4, v4, v3
	v_add_f32_e32 v5, v5, v4
	ds_bpermute_b32 v0, v0, v5
	s_waitcnt lgkmcnt(0)
	v_add_f32_e32 v0, v5, v0
	v_cndmask_b32_e32 v0, v0, v5, vcc
	ds_bpermute_b32 v10, v10, v0
	v_cmp_gt_u32_e32 vcc, 2, v7
	s_waitcnt lgkmcnt(0)
	v_add_f32_e32 v10, v0, v10
	v_cndmask_b32_e32 v0, v10, v0, vcc
	v_add_u32_e32 v10, -16, v9
	ds_bpermute_b32 v10, v10, v0
	v_cmp_gt_u32_e32 vcc, 4, v7
	s_waitcnt lgkmcnt(0)
	v_add_f32_e32 v10, v0, v10
	v_cndmask_b32_e32 v0, v10, v0, vcc
	v_subrev_u32_e32 v10, 32, v9
	ds_bpermute_b32 v10, v10, v0
	v_cmp_gt_u32_e32 vcc, 8, v7
	s_waitcnt lgkmcnt(0)
	v_add_f32_e32 v10, v0, v10
	v_cndmask_b32_e32 v0, v10, v0, vcc
	v_subrev_u32_e32 v10, 64, v9
	ds_bpermute_b32 v10, v10, v0
	v_cmp_gt_u32_e32 vcc, 16, v7
	v_add_u32_e32 v9, 0xffffff80, v9
	s_waitcnt lgkmcnt(0)
	v_add_f32_e32 v10, v0, v10
	v_cndmask_b32_e32 v0, v10, v0, vcc
	ds_bpermute_b32 v9, v9, v0
	v_cmp_eq_u32_e32 vcc, 63, v7
	s_waitcnt lgkmcnt(0)
	v_add_f32_e32 v9, v0, v9
	s_and_saveexec_b64 s[6:7], vcc
	v_lshl_add_u32 v10, v8, 2, 0
	v_add_u32_e32 v10, 0x16800, v10
	ds_write_b32 v10, v9
	s_or_b64 exec, exec, s[6:7]
	s_waitcnt lgkmcnt(0)
	s_barrier
	v_cmp_lt_i32_e32 vcc, 0, v8
	v_mov_b32_e32 v10, 0
	s_and_saveexec_b64 s[6:7], vcc
	s_cbranch_execz .LBB0_1302
	s_add_i32 s5, 0, 0x16800
	v_mov_b32_e32 v10, s5
	ds_read_b32 v10, v10
	s_waitcnt lgkmcnt(0)
	s_or_b64 exec, exec, s[6:7]
	v_cmp_lt_i32_e32 vcc, 1, v8
	s_and_saveexec_b64 s[6:7], vcc
	s_cbranch_execnz .LBB0_1303

.LBB0_1316:
	v_add_u32_e32 v0, s16, v240
	ds_read_b64_tr_b16 v[192:193], v0 offset:24576
	ds_read_b64_tr_b16 v[194:195], v0 offset:25088
	s_waitcnt lgkmcnt(9)
	v_mfma_f32_32x32x16_bf16 v[96:111], v[188:191], v[140:143], v[48:63]
	v_add_f32_e32 v2, v80, v81
	v_add_f32_e32 v2, v82, v2
	v_add_f32_e32 v2, v83, v2
	v_add_f32_e32 v2, v84, v2
	v_add_f32_e32 v2, v85, v2
	v_cvt_pk_bf16_f32 v156, v80, v81
	v_cvt_pk_bf16_f32 v157, v82, v83
	ds_read_b64_tr_b16 v[188:189], v0 offset:28672
	ds_read_b64_tr_b16 v[190:191], v0 offset:29184
	v_add_f32_e32 v2, v86, v2
	v_add_f32_e32 v2, v87, v2
	v_add_f32_e32 v2, v88, v2
	v_add_f32_e32 v2, v89, v2
	v_cvt_pk_bf16_f32 v158, v84, v85
	v_cvt_pk_bf16_f32 v159, v86, v87
	s_waitcnt lgkmcnt(10)
	v_mfma_f32_32x32x16_bf16 v[112:127], v[184:187], v[140:143], v[48:63]
	ds_read_b64_tr_b16 v[10:11], v0 offset:25600
	ds_read_b64_tr_b16 v[12:13], v0 offset:26112
	v_add_f32_e32 v2, v90, v2
	v_add_f32_e32 v2, v91, v2
	v_add_f32_e32 v2, v92, v2
	v_add_f32_e32 v2, v93, v2
	v_cvt_pk_bf16_f32 v152, v88, v89
	v_cvt_pk_bf16_f32 v153, v90, v91
	s_waitcnt lgkmcnt(11)
	v_mfma_f32_32x32x16_bf16 v[96:111], v[180:183], v[136:139], v[96:111]
	ds_read_b64_tr_b16 v[180:181], v0 offset:29696
	ds_read_b64_tr_b16 v[182:183], v0 offset:30208
	v_add_f32_e32 v2, v94, v2
	v_add_f32_e32 v2, v95, v2
	v_add_f32_e32 v2, v64, v2
	v_add_f32_e32 v2, v65, v2
	v_cvt_pk_bf16_f32 v154, v92, v93
	v_cvt_pk_bf16_f32 v155, v94, v95
	s_waitcnt lgkmcnt(12)
	v_mfma_f32_32x32x16_bf16 v[112:127], v[176:179], v[136:139], v[112:127]
	ds_read_b64_tr_b16 v[176:177], v0 offset:26624
	ds_read_b64_tr_b16 v[178:179], v0 offset:27136
	v_add_f32_e32 v2, v66, v2
	v_add_f32_e32 v2, v67, v2
	v_add_f32_e32 v2, v68, v2
	v_add_f32_e32 v6, v69, v2
	v_cvt_pk_bf16_f32 v148, v64, v65
	v_cvt_pk_bf16_f32 v149, v66, v67
	ds_read_b128 v[64:67], v200
	s_waitcnt lgkmcnt(13)
	v_mfma_f32_32x32x16_bf16 v[96:111], v[172:175], v[132:135], v[96:111]
	ds_read_b64_tr_b16 v[2:3], v0 offset:30720
	ds_read_b64_tr_b16 v[4:5], v0 offset:31232
	v_add_f32_e32 v6, v70, v6
	v_add_f32_e32 v6, v71, v6
	v_add_f32_e32 v6, v72, v6
	v_add_f32_e32 v14, v73, v6
	v_cvt_pk_bf16_f32 v150, v68, v69
	v_cvt_pk_bf16_f32 v151, v70, v71
	ds_read_b128 v[68:71], v200 offset:32
	s_waitcnt lgkmcnt(14)
	v_mfma_f32_32x32x16_bf16 v[112:127], v[168:171], v[132:135], v[112:127]
	ds_read_b64_tr_b16 v[6:7], v0 offset:27648
	ds_read_b64_tr_b16 v[8:9], v0 offset:28160
	v_add_f32_e32 v14, v74, v14
	v_add_f32_e32 v14, v75, v14
	v_add_f32_e32 v14, v76, v14
	v_add_f32_e32 v14, v77, v14
	v_cvt_pk_bf16_f32 v144, v72, v73
	v_cvt_pk_bf16_f32 v145, v74, v75
	ds_read_b128 v[72:75], v200 offset:128
	s_waitcnt lgkmcnt(14)
	v_mfma_f32_32x32x16_bf16 v[96:111], v[164:167], v[128:131], v[96:111]
	ds_read_b64_tr_b16 v[164:165], v0 offset:31744
	ds_read_b64_tr_b16 v[166:167], v0 offset:32256
	v_add_f32_e32 v0, v78, v14
	v_add_f32_e32 v0, v79, v0
	v_cvt_pk_bf16_f32 v146, v76, v77
	v_cvt_pk_bf16_f32 v147, v78, v79
	v_mfma_f32_32x32x16_bf16 v[112:127], v[160:163], v[128:131], v[112:127]
	s_add_i32 s16, s46, -2
	s_lshr_b32 s16, s16, 2
	s_and_b32 s22, s47, 0x18000
	v_mad_u64_u32 v[14:15], s[16:17], s16, v239, v[212:213]
	s_lshl_b32 s26, s22, 1
	v_lshl_add_u64 v[14:15], v[14:15], 0, s[26:27]
	s_add_i32 s16, s50, s74
	s_mov_b32 s17, m0
	s_mov_b32 m0, s16
	s_nop 0
	global_load_lds_dwordx4 v[14:15], off
	s_mov_b32 m0, s17
	s_add_i32 s16, s46, -4
	s_add_i32 s17, s47, 0xffff0000
	s_lshr_b32 s16, s16, 2
	s_and_b32 s22, s17, 0x18000
	v_mad_u64_u32 v[14:15], s[16:17], s16, v239, v[214:215]
	s_lshl_b32 s26, s22, 1
	v_lshl_add_u64 v[14:15], v[14:15], 0, s[26:27]
	s_add_i32 s16, s25, s75
	s_mov_b32 s17, m0
	s_mov_b32 m0, s16
	s_nop 0
	global_load_lds_dwordx4 v[14:15], off
	s_mov_b32 m0, s17
	v_add_f32_e32 v0, v241, v0
	s_waitcnt lgkmcnt(2)
	v_add_f32_e32 v82, v98, v66
	v_add_f32_e32 v83, v99, v67
	s_waitcnt lgkmcnt(1)
	v_add_f32_e32 v84, v100, v68
	v_add_f32_e32 v85, v101, v69
	s_waitcnt lgkmcnt(0)
	v_add_f32_e32 v14, v112, v72
	v_add_f32_e32 v15, v113, v73
	v_add_f32_e32 v66, v114, v74
	v_add_f32_e32 v67, v115, v75
	ds_read_b128 v[72:75], v200 offset:160
	v_add_f32_e32 v86, v102, v70
	v_add_f32_e32 v87, v103, v71
	v_add_f32_e32 v64, v96, v64
	v_add_f32_e32 v65, v97, v65
	v_max3_f32 v81, v82, v83, v15
	v_max_f32_e32 v80, v64, v65
	s_waitcnt lgkmcnt(0)
	v_add_f32_e32 v68, v116, v72
	v_add_f32_e32 v69, v117, v73
	v_add_f32_e32 v70, v118, v74
	v_add_f32_e32 v71, v119, v75
	ds_read_b128 v[72:75], v200 offset:64
	ds_read_b128 v[76:79], v200 offset:192
	v_max3_f32 v80, v80, v14, v66
	v_max3_f32 v80, v80, v67, v84
	v_max3_f32 v81, v81, v86, v87
	s_waitcnt lgkmcnt(1)
	v_add_f32_e32 v88, v104, v72
	v_add_f32_e32 v89, v105, v73
	s_waitcnt lgkmcnt(0)
	v_add_f32_e32 v72, v120, v76
	v_add_f32_e32 v73, v121, v77
	v_add_f32_e32 v90, v106, v74
	v_add_f32_e32 v91, v107, v75
	v_add_f32_e32 v74, v122, v78
	v_add_f32_e32 v75, v123, v79
	ds_read_b128 v[76:79], v200 offset:96
	ds_read_b128 v[94:97], v200 offset:224
	v_max3_f32 v80, v80, v85, v68
	v_max3_f32 v81, v81, v70, v71
	v_max3_f32 v80, v80, v69, v88
	v_max3_f32 v81, v81, v90, v91
	s_waitcnt lgkmcnt(1)
	v_add_f32_e32 v92, v108, v76
	v_add_f32_e32 v93, v109, v77
	s_waitcnt lgkmcnt(0)
	v_add_f32_e32 v76, v124, v94
	v_add_f32_e32 v77, v125, v95
	v_add_f32_e32 v94, v110, v78
	v_add_f32_e32 v95, v111, v79
	v_max3_f32 v80, v80, v89, v72
	v_max3_f32 v81, v81, v74, v75
	v_add_f32_e32 v78, v126, v96
	v_add_f32_e32 v79, v127, v97
	v_max3_f32 v80, v80, v73, v92
	v_max3_f32 v81, v81, v94, v95
	v_max3_f32 v80, v80, v93, v76
	v_max3_f32 v81, v81, v78, v79
	v_max3_f32 v80, v80, v77, v81
	v_mov_b32_e32 v81, v80
	s_nop 1
	v_permlane32_swap_b32_e32 v80, v81
	v_max_f32_e32 v80, v80, v81
	v_cmp_lt_f32_e32 vcc, s36, v80
	s_cmp_lg_u64 vcc, 0
	s_cselect_b64 s[16:17], -1, 0
	s_cbranch_vccnz .LBB0_1324

.LBB0_1319:
	s_add_i32 s16, s25, 0x2000
	s_cmpk_lg_i32 s25, 0x4000
	s_cselect_b32 s78, s16, 0
	v_add_u32_e32 v14, s50, v240
	ds_read_b64_tr_b16 v[168:169], v14 offset:24576
	ds_read_b64_tr_b16 v[170:171], v14 offset:25088
	s_waitcnt lgkmcnt(9)
	v_mfma_f32_32x32x16_bf16 v[96:111], v[112:115], v[140:143], v[48:63]
	v_add_f32_e32 v2, v80, v81
	v_add_f32_e32 v2, v82, v2
	v_add_f32_e32 v2, v83, v2
	v_add_f32_e32 v2, v84, v2
	v_add_f32_e32 v2, v85, v2
	v_cvt_pk_bf16_f32 v156, v80, v81
	v_cvt_pk_bf16_f32 v157, v82, v83
	ds_read_b64_tr_b16 v[164:165], v14 offset:28672
	ds_read_b64_tr_b16 v[166:167], v14 offset:29184
	v_add_f32_e32 v2, v86, v2
	v_add_f32_e32 v2, v87, v2
	v_add_f32_e32 v2, v88, v2
	v_add_f32_e32 v2, v89, v2
	v_cvt_pk_bf16_f32 v158, v84, v85
	v_cvt_pk_bf16_f32 v159, v86, v87
	s_waitcnt lgkmcnt(10)
	v_mfma_f32_32x32x16_bf16 v[112:127], v[160:163], v[140:143], v[48:63]
	ds_read_b64_tr_b16 v[10:11], v14 offset:25600
	ds_read_b64_tr_b16 v[12:13], v14 offset:26112
	v_add_f32_e32 v2, v90, v2
	v_add_f32_e32 v2, v91, v2
	v_add_f32_e32 v2, v92, v2
	v_add_f32_e32 v2, v93, v2
	v_cvt_pk_bf16_f32 v152, v88, v89
	v_cvt_pk_bf16_f32 v153, v90, v91
	s_waitcnt lgkmcnt(11)
	v_mfma_f32_32x32x16_bf16 v[96:111], v[192:195], v[136:139], v[96:111]
	ds_read_b64_tr_b16 v[160:161], v14 offset:29696
	ds_read_b64_tr_b16 v[162:163], v14 offset:30208
	v_add_f32_e32 v2, v94, v2
	v_add_f32_e32 v2, v95, v2
	v_add_f32_e32 v2, v64, v2
	v_add_f32_e32 v2, v65, v2
	v_cvt_pk_bf16_f32 v154, v92, v93
	v_cvt_pk_bf16_f32 v155, v94, v95
	s_waitcnt lgkmcnt(12)
	v_mfma_f32_32x32x16_bf16 v[112:127], v[188:191], v[136:139], v[112:127]
	ds_read_b64_tr_b16 v[196:197], v14 offset:26624
	ds_read_b64_tr_b16 v[198:199], v14 offset:27136
	v_add_f32_e32 v2, v66, v2
	v_add_f32_e32 v2, v67, v2
	v_add_f32_e32 v2, v68, v2
	v_add_f32_e32 v6, v69, v2
	v_cvt_pk_bf16_f32 v148, v64, v65
	v_cvt_pk_bf16_f32 v149, v66, v67
	ds_read_b128 v[64:67], v200 offset:256
	s_waitcnt lgkmcnt(13)
	v_mfma_f32_32x32x16_bf16 v[96:111], v[184:187], v[132:135], v[96:111]
	ds_read_b64_tr_b16 v[2:3], v14 offset:30720
	ds_read_b64_tr_b16 v[4:5], v14 offset:31232
	v_add_f32_e32 v6, v70, v6
	v_add_f32_e32 v6, v71, v6
	v_add_f32_e32 v6, v72, v6
	v_add_f32_e32 v15, v73, v6
	v_cvt_pk_bf16_f32 v150, v68, v69
	v_cvt_pk_bf16_f32 v151, v70, v71
	ds_read_b128 v[68:71], v200 offset:288
	s_waitcnt lgkmcnt(14)
	v_mfma_f32_32x32x16_bf16 v[112:127], v[180:183], v[132:135], v[112:127]
	ds_read_b64_tr_b16 v[6:7], v14 offset:27648
	ds_read_b64_tr_b16 v[8:9], v14 offset:28160
	v_add_f32_e32 v15, v74, v15
	v_add_f32_e32 v15, v75, v15
	v_add_f32_e32 v15, v76, v15
	v_add_f32_e32 v15, v77, v15
	v_cvt_pk_bf16_f32 v144, v72, v73
	v_cvt_pk_bf16_f32 v145, v74, v75
	ds_read_b128 v[72:75], v200 offset:384
	s_waitcnt lgkmcnt(14)
	v_mfma_f32_32x32x16_bf16 v[96:111], v[176:179], v[128:131], v[96:111]
	ds_read_b64_tr_b16 v[192:193], v14 offset:31744
	ds_read_b64_tr_b16 v[194:195], v14 offset:32256
	v_add_f32_e32 v14, v78, v15
	v_add_f32_e32 v14, v79, v14
	v_add_f32_e32 v80, 0, v14
	v_cvt_pk_bf16_f32 v146, v76, v77
	v_cvt_pk_bf16_f32 v147, v78, v79
	v_mfma_f32_32x32x16_bf16 v[112:127], v[172:175], v[128:131], v[112:127]
	s_add_i32 s16, s46, -1
	s_add_i32 s17, s47, 0xfffe8000
	s_lshr_b32 s16, s16, 2
	s_and_b32 s22, s17, 0x18000
	v_mad_u64_u32 v[14:15], s[16:17], s16, v239, v[212:213]
	s_lshl_b32 s26, s22, 1
	v_lshl_add_u64 v[14:15], v[14:15], 0, s[26:27]
	s_add_i32 s16, s25, s74
	s_mov_b32 s17, m0
	s_mov_b32 m0, s16
	s_nop 0
	global_load_lds_dwordx4 v[14:15], off
	s_mov_b32 m0, s17
	s_add_i32 s50, s46, -3
	s_add_i32 s17, s47, 0xffff8000
	s_lshr_b32 s16, s50, 2
	s_and_b32 s22, s17, 0x18000
	v_mad_u64_u32 v[14:15], s[16:17], s16, v239, v[214:215]
	s_lshl_b32 s26, s22, 1
	v_lshl_add_u64 v[14:15], v[14:15], 0, s[26:27]
	s_add_i32 s16, s78, s75
	s_mov_b32 s17, m0
	s_mov_b32 m0, s16
	s_nop 0
	global_load_lds_dwordx4 v[14:15], off
	s_mov_b32 m0, s17
	v_add_f32_e32 v241, v0, v80
	s_waitcnt lgkmcnt(2)
	v_add_f32_e32 v82, v98, v66
	v_add_f32_e32 v83, v99, v67
	s_waitcnt lgkmcnt(1)
	v_add_f32_e32 v84, v100, v68
	v_add_f32_e32 v85, v101, v69
	s_waitcnt lgkmcnt(0)
	v_add_f32_e32 v14, v112, v72
	v_add_f32_e32 v15, v113, v73
	v_add_f32_e32 v66, v114, v74
	v_add_f32_e32 v67, v115, v75
	ds_read_b128 v[72:75], v200 offset:416
	v_add_f32_e32 v86, v102, v70
	v_add_f32_e32 v87, v103, v71
	v_add_f32_e32 v64, v96, v64
	v_add_f32_e32 v65, v97, v65
	s_waitcnt lgkmcnt(0)
	v_add_f32_e32 v68, v116, v72
	v_add_f32_e32 v69, v117, v73
	v_add_f32_e32 v70, v118, v74
	v_add_f32_e32 v71, v119, v75
	ds_read_b128 v[72:75], v200 offset:320
	ds_read_b128 v[76:79], v200 offset:448
	v_max_f32_e32 v81, v64, v65
	v_max3_f32 v81, v81, v14, v66
	v_max3_f32 v81, v81, v67, v84
	s_waitcnt lgkmcnt(1)
	v_add_f32_e32 v88, v104, v72
	v_add_f32_e32 v89, v105, v73
	s_waitcnt lgkmcnt(0)
	v_add_f32_e32 v72, v120, v76
	v_add_f32_e32 v73, v121, v77
	v_add_f32_e32 v90, v106, v74
	v_add_f32_e32 v91, v107, v75
	v_add_f32_e32 v74, v122, v78
	v_add_f32_e32 v75, v123, v79
	ds_read_b128 v[76:79], v200 offset:352
	ds_read_b128 v[94:97], v200 offset:480
	v_max3_f32 v81, v81, v85, v68
	v_max3_f32 v81, v81, v69, v88
	v_max3_f32 v81, v81, v89, v72
	s_waitcnt lgkmcnt(1)
	v_add_f32_e32 v92, v108, v76
	v_add_f32_e32 v93, v109, v77
	s_waitcnt lgkmcnt(0)
	v_add_f32_e32 v76, v124, v94
	v_add_f32_e32 v77, v125, v95
	v_add_f32_e32 v94, v110, v78
	v_add_f32_e32 v95, v111, v79
	v_add_f32_e32 v78, v126, v96
	v_add_f32_e32 v79, v127, v97
	v_max3_f32 v96, v82, v83, v15
	v_max3_f32 v96, v96, v86, v87
	v_max3_f32 v96, v96, v70, v71
	v_max3_f32 v96, v96, v90, v91
	v_max3_f32 v96, v96, v74, v75
	v_max3_f32 v81, v81, v73, v92
	v_max3_f32 v96, v96, v94, v95
	v_max3_f32 v81, v81, v93, v76
	v_max3_f32 v96, v96, v78, v79
	v_max3_f32 v0, v81, v77, v96
	v_mov_b32_e32 v80, v0
	s_nop 1
	v_permlane32_swap_b32_e32 v0, v80
	v_max_f32_e32 v0, v0, v80
	v_cmp_lt_f32_e32 vcc, s36, v0
	s_cmp_lg_u64 vcc, 0
	s_cselect_b64 s[16:17], -1, 0
	s_cbranch_vccnz .LBB0_1327

.LBB0_1327:
	v_max_f32_e32 v0, 0, v0
	v_exp_f32_e64 v80, -v0
	v_add_f32_e32 v229, v229, v0
	v_xor_b32_e32 v48, 0x80000000, v229
	v_mov_b32_e32 v49, v48
	v_mov_b32_e32 v50, v48
	v_mov_b32_e32 v51, v48
	v_mov_b32_e32 v52, v48
	v_mov_b32_e32 v53, v48
	v_mov_b32_e32 v54, v48
	v_mov_b32_e32 v55, v48
	v_mov_b32_e32 v56, v48
	v_mov_b32_e32 v57, v48
	v_mov_b32_e32 v58, v48
	v_mov_b32_e32 v59, v48
	v_mov_b32_e32 v60, v48
	v_mov_b32_e32 v61, v48
	v_mov_b32_e32 v62, v48
	v_mov_b32_e32 v63, v48
	s_and_saveexec_b64 s[22:23], s[2:3]
	ds_write_b32 v226, v80 offset:49152
	s_or_b64 exec, exec, s[22:23]
	v_sub_f32_e32 v64, v64, v0
	v_sub_f32_e32 v65, v65, v0
	v_sub_f32_e32 v82, v82, v0
	v_sub_f32_e32 v83, v83, v0
	v_sub_f32_e32 v84, v84, v0
	v_sub_f32_e32 v85, v85, v0
	v_sub_f32_e32 v86, v86, v0
	v_sub_f32_e32 v87, v87, v0
	v_sub_f32_e32 v88, v88, v0
	v_sub_f32_e32 v89, v89, v0
	v_sub_f32_e32 v90, v90, v0
	v_sub_f32_e32 v91, v91, v0
	v_sub_f32_e32 v92, v92, v0
	v_sub_f32_e32 v93, v93, v0
	v_sub_f32_e32 v94, v94, v0
	v_sub_f32_e32 v95, v95, v0
	v_sub_f32_e32 v14, v14, v0
	v_sub_f32_e32 v15, v15, v0
	v_sub_f32_e32 v66, v66, v0
	v_sub_f32_e32 v67, v67, v0
	v_sub_f32_e32 v68, v68, v0
	v_sub_f32_e32 v69, v69, v0
	v_sub_f32_e32 v70, v70, v0
	v_sub_f32_e32 v71, v71, v0
	v_sub_f32_e32 v72, v72, v0
	v_sub_f32_e32 v73, v73, v0
	v_sub_f32_e32 v74, v74, v0
	v_sub_f32_e32 v75, v75, v0
	v_sub_f32_e32 v76, v76, v0
	v_sub_f32_e32 v77, v77, v0
	v_sub_f32_e32 v78, v78, v0
	v_sub_f32_e32 v79, v79, v0
	v_mul_f32_e32 v241, v241, v80
	s_branch .LBB0_1320

.LBB0_1333:
	v_add_u32_e32 v15, s25, v240
	ds_read_b64_tr_b16 v[192:193], v15 offset:24576
	ds_read_b64_tr_b16 v[194:195], v15 offset:25088
	s_waitcnt lgkmcnt(3)
	v_mfma_f32_32x32x16_bf16 v[112:127], v[188:191], v[140:143], v[48:63]
	v_add_f32_e32 v2, v80, v81
	v_add_f32_e32 v2, v82, v2
	v_add_f32_e32 v2, v83, v2
	v_add_f32_e32 v2, v84, v2
	v_add_f32_e32 v2, v85, v2
	v_cvt_pk_bf16_f32 v156, v80, v81
	v_cvt_pk_bf16_f32 v157, v82, v83
	ds_read_b64_tr_b16 v[188:189], v15 offset:28672
	ds_read_b64_tr_b16 v[190:191], v15 offset:29184
	s_waitcnt lgkmcnt(4)
	v_mfma_f32_32x32x16_bf16 v[96:111], v[184:187], v[140:143], v[48:63]
	v_add_f32_e32 v2, v86, v2
	v_add_f32_e32 v2, v87, v2
	v_add_f32_e32 v2, v88, v2
	v_add_f32_e32 v6, v89, v2
	v_cvt_pk_bf16_f32 v158, v84, v85
	v_cvt_pk_bf16_f32 v159, v86, v87
	ds_read_b64_tr_b16 v[2:3], v15 offset:25600
	ds_read_b64_tr_b16 v[4:5], v15 offset:26112
	s_waitcnt lgkmcnt(11)
	v_mfma_f32_32x32x16_bf16 v[112:127], v[180:183], v[136:139], v[112:127]
	v_add_f32_e32 v6, v90, v6
	v_add_f32_e32 v6, v91, v6
	v_add_f32_e32 v6, v92, v6
	v_add_f32_e32 v10, v93, v6
	v_cvt_pk_bf16_f32 v152, v88, v89
	v_cvt_pk_bf16_f32 v153, v90, v91
	ds_read_b64_tr_b16 v[6:7], v15 offset:29696
	ds_read_b64_tr_b16 v[8:9], v15 offset:30208
	s_waitcnt lgkmcnt(12)
	v_mfma_f32_32x32x16_bf16 v[96:111], v[176:179], v[136:139], v[96:111]
	v_add_f32_e32 v10, v94, v10
	v_add_f32_e32 v10, v95, v10
	v_add_f32_e32 v10, v64, v10
	v_add_f32_e32 v80, v65, v10
	v_cvt_pk_bf16_f32 v154, v92, v93
	v_cvt_pk_bf16_f32 v155, v94, v95
	ds_read_b64_tr_b16 v[10:11], v15 offset:26624
	ds_read_b64_tr_b16 v[12:13], v15 offset:27136
	s_waitcnt lgkmcnt(13)
	v_mfma_f32_32x32x16_bf16 v[112:127], v[172:175], v[132:135], v[112:127]
	v_add_f32_e32 v80, v66, v80
	v_add_f32_e32 v80, v67, v80
	v_add_f32_e32 v80, v68, v80
	v_add_f32_e32 v80, v69, v80
	v_cvt_pk_bf16_f32 v148, v64, v65
	v_cvt_pk_bf16_f32 v149, v66, v67
	ds_read_b64_tr_b16 v[196:197], v15 offset:30720
	ds_read_b64_tr_b16 v[198:199], v15 offset:31232
	s_waitcnt lgkmcnt(14)
	v_mfma_f32_32x32x16_bf16 v[96:111], v[168:171], v[132:135], v[96:111]
	v_add_f32_e32 v64, v70, v80
	v_add_f32_e32 v64, v71, v64
	v_add_f32_e32 v64, v72, v64
	v_add_f32_e32 v64, v73, v64
	v_cvt_pk_bf16_f32 v150, v68, v69
	v_cvt_pk_bf16_f32 v151, v70, v71
	ds_read_b64_tr_b16 v[200:201], v15 offset:27648
	ds_read_b64_tr_b16 v[202:203], v15 offset:28160
	s_waitcnt lgkmcnt(14)
	v_mfma_f32_32x32x16_bf16 v[112:127], v[164:167], v[128:131], v[112:127]
	v_add_f32_e32 v64, v74, v64
	v_add_f32_e32 v64, v75, v64
	v_add_f32_e32 v64, v76, v64
	v_add_f32_e32 v64, v77, v64
	v_cvt_pk_bf16_f32 v144, v72, v73
	v_cvt_pk_bf16_f32 v145, v74, v75
	ds_read_b64_tr_b16 v[204:205], v15 offset:31744
	ds_read_b64_tr_b16 v[206:207], v15 offset:32256
	v_mfma_f32_32x32x16_bf16 v[96:111], v[160:163], v[128:131], v[96:111]
	v_add_f32_e32 v15, v78, v64
	v_add_f32_e32 v15, v79, v15
	v_cvt_pk_bf16_f32 v146, v76, v77
	v_cvt_pk_bf16_f32 v147, v78, v79
	s_add_i32 s4, s58, 1
	s_cmp_ge_u32 s4, s77
	s_cselect_b64 s[22:23], -1, 0
	s_and_b64 vcc, exec, s[22:23]
	s_cbranch_vccnz .LBB0_1335
	s_add_i32 s5, s79, 0x18000
	s_lshr_b32 s4, s4, 2
	s_and_b32 s24, s5, 0x18000
	v_mad_u64_u32 v[64:65], s[4:5], s4, v239, v[212:213]
	s_lshl_b32 s26, s24, 1
	v_lshl_add_u64 v[64:65], v[64:65], 0, s[26:27]
	s_add_i32 s4, s78, s74
	s_mov_b32 s5, m0
	s_mov_b32 m0, s4
	s_nop 0
	global_load_lds_dwordx4 v[64:65], off
	s_mov_b32 m0, s5

.LBB0_1337:
	v_max_f32_e32 v96, v81, v81
	v_max_f32_e32 v97, v80, v80
	v_max_f32_e32 v96, v97, v96
	v_max3_f32 v97, v82, v83, v65
	v_max3_f32 v96, v96, v64, v66
	v_max3_f32 v96, v96, v67, v84
	v_max3_f32 v97, v97, v86, v87
	v_max3_f32 v96, v96, v85, v68
	v_max3_f32 v97, v97, v70, v71
	v_max3_f32 v96, v96, v69, v88
	v_max3_f32 v97, v97, v90, v91
	v_max3_f32 v96, v96, v89, v72
	v_max3_f32 v97, v97, v74, v75
	v_max3_f32 v96, v96, v73, v92
	v_max3_f32 v97, v97, v94, v95
	v_max3_f32 v96, v96, v93, v76
	v_max3_f32 v97, v97, v78, v79
	v_max3_f32 v96, v96, v77, v97
	v_mov_b32_e32 v97, v96
	s_nop 1
	v_permlane32_swap_b32_e32 v96, v97
	v_max_f32_e32 v96, v96, v97
	v_cmp_lt_f32_e32 vcc, s36, v96
	s_cmp_lg_u64 vcc, 0
	v_add_f32_e32 v15, v241, v15
	s_cselect_b64 s[4:5], -1, 0
	s_cbranch_vccnz .LBB0_1375

.LBB0_1352:
	v_add_f32_e32 v241, v15, v241
	v_max_f32_e32 v15, v81, v81
	v_max_f32_e32 v96, v80, v80
	v_max_f32_e32 v15, v96, v15
	v_max3_f32 v96, v82, v83, v65
	v_max3_f32 v15, v15, v64, v66
	v_max3_f32 v15, v15, v67, v84
	v_max3_f32 v96, v96, v86, v87
	v_max3_f32 v15, v15, v85, v68
	v_max3_f32 v96, v96, v70, v71
	v_max3_f32 v15, v15, v69, v88
	v_max3_f32 v96, v96, v90, v91
	v_max3_f32 v15, v15, v89, v72
	v_max3_f32 v96, v96, v74, v75
	v_max3_f32 v15, v15, v73, v92
	v_max3_f32 v96, v96, v94, v95
	v_max3_f32 v15, v15, v93, v76
	v_max3_f32 v96, v96, v78, v79
	v_max3_f32 v15, v15, v77, v96
	v_mov_b32_e32 v96, v15
	s_nop 1
	v_permlane32_swap_b32_e32 v15, v96
	v_max_f32_e32 v15, v15, v96
	v_cmp_lt_f32_e32 vcc, s36, v15
	s_cmp_lg_u64 vcc, 0
	s_cselect_b64 s[58:59], -1, 0
	s_cbranch_vccnz .LBB0_1378

.LBB0_1378:
	v_max_f32_e32 v15, 0, v15
	v_exp_f32_e64 v96, -v15
	v_add_f32_e32 v229, v229, v15
	v_xor_b32_e32 v48, 0x80000000, v229
	v_mov_b32_e32 v49, v48
	v_mov_b32_e32 v50, v48
	v_mov_b32_e32 v51, v48
	v_mov_b32_e32 v52, v48
	v_mov_b32_e32 v53, v48
	v_mov_b32_e32 v54, v48
	v_mov_b32_e32 v55, v48
	v_mov_b32_e32 v56, v48
	v_mov_b32_e32 v57, v48
	v_mov_b32_e32 v58, v48
	v_mov_b32_e32 v59, v48
	v_mov_b32_e32 v60, v48
	v_mov_b32_e32 v61, v48
	v_mov_b32_e32 v62, v48
	v_mov_b32_e32 v63, v48
	s_and_saveexec_b64 s[4:5], s[2:3]
	ds_write_b32 v226, v96 offset:49152
	s_or_b64 exec, exec, s[4:5]
	v_sub_f32_e32 v95, v95, v15
	v_sub_f32_e32 v94, v94, v15
	v_sub_f32_e32 v93, v93, v15
	v_sub_f32_e32 v92, v92, v15
	v_sub_f32_e32 v91, v91, v15
	v_sub_f32_e32 v90, v90, v15
	v_sub_f32_e32 v89, v89, v15
	v_sub_f32_e32 v88, v88, v15
	v_sub_f32_e32 v87, v87, v15
	v_sub_f32_e32 v86, v86, v15
	v_sub_f32_e32 v85, v85, v15
	v_sub_f32_e32 v84, v84, v15
	v_sub_f32_e32 v83, v83, v15
	v_sub_f32_e32 v82, v82, v15
	v_sub_f32_e32 v81, v81, v15
	v_sub_f32_e32 v80, v80, v15
	v_sub_f32_e32 v79, v79, v15
	v_sub_f32_e32 v78, v78, v15
	v_sub_f32_e32 v77, v77, v15
	v_sub_f32_e32 v76, v76, v15
	v_sub_f32_e32 v75, v75, v15
	v_sub_f32_e32 v74, v74, v15
	v_sub_f32_e32 v73, v73, v15
	v_sub_f32_e32 v72, v72, v15
	v_sub_f32_e32 v71, v71, v15
	v_sub_f32_e32 v70, v70, v15
	v_sub_f32_e32 v69, v69, v15
	v_sub_f32_e32 v68, v68, v15
	v_sub_f32_e32 v67, v67, v15
	v_sub_f32_e32 v66, v66, v15
	v_sub_f32_e32 v65, v65, v15
	v_sub_f32_e32 v64, v64, v15
	v_mul_f32_e32 v241, v241, v96
	s_branch .LBB0_1353

.LBB0_1382:
	v_add_u32_e32 v0, s64, v240
	ds_read_b64_tr_b16 v[6:7], v0 offset:24576
	ds_read_b64_tr_b16 v[8:9], v0 offset:25088
	v_add_f32_e32 v2, v80, v81
	v_add_f32_e32 v2, v82, v2
	v_add_f32_e32 v2, v83, v2
	v_add_f32_e32 v2, v84, v2
	v_add_f32_e32 v10, v85, v2
	v_cvt_pk_bf16_f32 v156, v80, v81
	v_cvt_pk_bf16_f32 v157, v82, v83
	s_waitcnt lgkmcnt(3)
	v_mfma_f32_32x32x16_bf16 v[96:111], v[188:191], v[140:143], v[48:63]
	ds_read_b64_tr_b16 v[2:3], v0 offset:28672
	ds_read_b64_tr_b16 v[4:5], v0 offset:29184
	s_waitcnt lgkmcnt(4)
	v_mfma_f32_32x32x16_bf16 v[48:63], v[184:187], v[140:143], v[48:63]
	v_add_f32_e32 v10, v86, v10
	v_add_f32_e32 v10, v87, v10
	v_add_f32_e32 v10, v88, v10
	v_add_f32_e32 v14, v89, v10
	v_cvt_pk_bf16_f32 v158, v84, v85
	v_cvt_pk_bf16_f32 v159, v86, v87
	ds_read_b64_tr_b16 v[10:11], v0 offset:25600
	ds_read_b64_tr_b16 v[12:13], v0 offset:26112
	v_add_f32_e32 v14, v90, v14
	v_add_f32_e32 v14, v91, v14
	v_add_f32_e32 v14, v92, v14
	v_add_f32_e32 v14, v93, v14
	v_cvt_pk_bf16_f32 v152, v88, v89
	v_cvt_pk_bf16_f32 v153, v90, v91
	v_mfma_f32_32x32x16_bf16 v[96:111], v[180:183], v[136:139], v[96:111]
	ds_read_b64_tr_b16 v[112:113], v0 offset:29696
	ds_read_b64_tr_b16 v[114:115], v0 offset:30208
	v_mfma_f32_32x32x16_bf16 v[48:63], v[176:179], v[136:139], v[48:63]
	v_add_f32_e32 v14, v94, v14
	v_add_f32_e32 v14, v95, v14
	v_add_f32_e32 v14, v64, v14
	v_add_f32_e32 v14, v65, v14
	v_cvt_pk_bf16_f32 v154, v92, v93
	v_cvt_pk_bf16_f32 v155, v94, v95
	ds_read_b64_tr_b16 v[116:117], v0 offset:26624
	ds_read_b64_tr_b16 v[118:119], v0 offset:27136
	v_add_f32_e32 v14, v66, v14
	v_add_f32_e32 v14, v67, v14
	v_add_f32_e32 v14, v68, v14
	v_add_f32_e32 v14, v69, v14
	v_cvt_pk_bf16_f32 v148, v64, v65
	v_cvt_pk_bf16_f32 v149, v66, v67
	v_mfma_f32_32x32x16_bf16 v[96:111], v[172:175], v[132:135], v[96:111]
	ds_read_b64_tr_b16 v[120:121], v0 offset:30720
	ds_read_b64_tr_b16 v[122:123], v0 offset:31232
	v_mfma_f32_32x32x16_bf16 v[48:63], v[168:171], v[132:135], v[48:63]
	v_add_f32_e32 v14, v70, v14
	v_add_f32_e32 v14, v71, v14
	v_add_f32_e32 v14, v72, v14
	v_add_f32_e32 v14, v73, v14
	v_cvt_pk_bf16_f32 v150, v68, v69
	v_cvt_pk_bf16_f32 v151, v70, v71
	ds_read_b64_tr_b16 v[124:125], v0 offset:27648
	ds_read_b64_tr_b16 v[126:127], v0 offset:28160
	v_add_f32_e32 v14, v74, v14
	v_add_f32_e32 v14, v75, v14
	v_add_f32_e32 v14, v76, v14
	v_add_f32_e32 v14, v77, v14
	v_cvt_pk_bf16_f32 v144, v72, v73
	v_cvt_pk_bf16_f32 v145, v74, v75
	v_mfma_f32_32x32x16_bf16 v[96:111], v[164:167], v[128:131], v[96:111]
	ds_read_b64_tr_b16 v[132:133], v0 offset:31744
	ds_read_b64_tr_b16 v[134:135], v0 offset:32256
	v_mfma_f32_32x32x16_bf16 v[48:63], v[160:163], v[128:131], v[48:63]
	v_add_f32_e32 v0, v78, v14
	v_add_f32_e32 v0, v79, v0
	v_cvt_pk_bf16_f32 v146, v76, v77
	v_cvt_pk_bf16_f32 v147, v78, v79
	v_lshl_add_u32 v14, s76, 2, v225
	v_add_u32_e32 v15, 0xffffff00, v14
	v_add_u32_e32 v68, 0xffffff80, v14
	ds_read_b128 v[64:67], v15
	ds_read_b128 v[68:71], v68
	v_add_u32_e32 v15, 0xffffff20, v14
	v_add_u32_e32 v76, 0xffffffa0, v14
	ds_read_b128 v[72:75], v15
	ds_read_b128 v[76:79], v76
	v_add_u32_e32 v15, 0xffffff40, v14
	v_subrev_u32_e32 v84, 64, v14
	ds_read_b128 v[80:83], v15
	ds_read_b128 v[84:87], v84
	v_add_u32_e32 v15, 0xffffff60, v14
	v_subrev_u32_e32 v14, 32, v14
	ds_read_b128 v[88:91], v15
	ds_read_b128 v[92:95], v14
	s_waitcnt lgkmcnt(7)
	v_add_f32_e32 v14, v98, v66
	v_add_f32_e32 v15, v99, v67
	v_or_b32_e32 v67, 0xe0, v221
	s_waitcnt lgkmcnt(6)
	v_add_f32_e32 v48, v48, v68
	v_add_f32_e32 v49, v49, v69
	v_or_b32_e32 v66, 0xc0, v221
	v_cmp_le_i32_e32 vcc, v67, v227
	v_add_f32_e32 v64, v96, v64
	v_add_f32_e32 v65, v97, v65
	v_add_f32_e32 v50, v50, v70
	v_add_f32_e32 v51, v51, v71
	v_cndmask_b32_e32 v48, v238, v48, vcc
	v_cmp_lt_i32_e32 vcc, v66, v227
	s_waitcnt lgkmcnt(5)
	v_add_f32_e32 v72, v100, v72
	v_add_f32_e32 v73, v101, v73
	s_waitcnt lgkmcnt(4)
	v_add_f32_e32 v52, v52, v76
	v_add_f32_e32 v53, v53, v77
	v_cndmask_b32_e32 v65, v238, v65, vcc
	v_cmp_le_i32_e32 vcc, v66, v227
	v_or_b32_e32 v66, 0xe1, v221
	v_add_f32_e32 v74, v102, v74
	v_add_f32_e32 v75, v103, v75
	v_cndmask_b32_e32 v64, v238, v64, vcc
	v_cmp_le_i32_e32 vcc, v66, v227
	v_or_b32_e32 v66, 0xc2, v221
	v_add_f32_e32 v54, v54, v78
	v_add_f32_e32 v55, v55, v79
	v_cndmask_b32_e32 v49, v238, v49, vcc
	v_cmp_le_i32_e32 vcc, v66, v227
	s_waitcnt lgkmcnt(3)
	v_add_f32_e32 v80, v104, v80
	v_add_f32_e32 v81, v105, v81
	s_waitcnt lgkmcnt(2)
	v_add_f32_e32 v56, v56, v84
	v_add_f32_e32 v57, v57, v85
	v_cndmask_b32_e32 v66, v238, v14, vcc
	v_or_b32_e32 v14, 0xe2, v221
	v_cmp_le_i32_e32 vcc, v14, v227
	v_or_b32_e32 v14, 0xc3, v221
	v_add_f32_e32 v82, v106, v82
	v_add_f32_e32 v83, v107, v83
	v_cndmask_b32_e32 v50, v238, v50, vcc
	v_cmp_le_i32_e32 vcc, v14, v227
	v_or_b32_e32 v14, 0xe3, v221
	v_add_f32_e32 v58, v58, v86
	v_add_f32_e32 v59, v59, v87
	v_cndmask_b32_e32 v67, v238, v15, vcc
	v_cmp_le_i32_e32 vcc, v14, v227
	v_or_b32_e32 v14, 0xc8, v221
	s_waitcnt lgkmcnt(1)
	v_add_f32_e32 v88, v108, v88
	v_add_f32_e32 v89, v109, v89
	v_cndmask_b32_e32 v51, v238, v51, vcc
	v_cmp_le_i32_e32 vcc, v14, v227
	v_or_b32_e32 v14, 0xe8, v221
	s_waitcnt lgkmcnt(0)
	v_add_f32_e32 v60, v60, v92
	v_add_f32_e32 v61, v61, v93
	v_cndmask_b32_e32 v68, v238, v72, vcc
	v_cmp_le_i32_e32 vcc, v14, v227
	v_or_b32_e32 v14, 0xc9, v221
	v_add_f32_e32 v90, v110, v90
	v_add_f32_e32 v91, v111, v91
	v_cndmask_b32_e32 v52, v238, v52, vcc
	v_cmp_le_i32_e32 vcc, v14, v227
	v_or_b32_e32 v14, 0xe9, v221
	v_add_f32_e32 v62, v62, v94
	v_add_f32_e32 v63, v63, v95
	v_cndmask_b32_e32 v69, v238, v73, vcc
	v_cmp_le_i32_e32 vcc, v14, v227
	v_or_b32_e32 v14, 0xca, v221
	v_max3_f32 v15, v66, v67, v49
	v_cndmask_b32_e32 v53, v238, v53, vcc
	v_cmp_le_i32_e32 vcc, v14, v227
	v_or_b32_e32 v14, 0xea, v221
	v_add_f32_e32 v0, v241, v0
	v_cndmask_b32_e32 v70, v238, v74, vcc
	v_cmp_le_i32_e32 vcc, v14, v227
	v_or_b32_e32 v14, 0xcb, v221
	s_nop 0
	v_cndmask_b32_e32 v54, v238, v54, vcc
	v_cmp_le_i32_e32 vcc, v14, v227
	v_or_b32_e32 v14, 0xeb, v221
	s_nop 0
	v_cndmask_b32_e32 v71, v238, v75, vcc
	v_cmp_le_i32_e32 vcc, v14, v227
	v_or_b32_e32 v14, 0xd0, v221
	v_max3_f32 v15, v15, v70, v71
	v_cndmask_b32_e32 v55, v238, v55, vcc
	v_cmp_le_i32_e32 vcc, v14, v227
	v_or_b32_e32 v14, 0xf0, v221
	v_max3_f32 v15, v15, v54, v55
	v_cndmask_b32_e32 v72, v238, v80, vcc
	v_cmp_le_i32_e32 vcc, v14, v227
	v_or_b32_e32 v14, 0xd1, v221
	s_nop 0
	v_cndmask_b32_e32 v56, v238, v56, vcc
	v_cmp_le_i32_e32 vcc, v14, v227
	v_or_b32_e32 v14, 0xf1, v221
	s_nop 0
	v_cndmask_b32_e32 v73, v238, v81, vcc
	v_cmp_le_i32_e32 vcc, v14, v227
	v_or_b32_e32 v14, 0xd2, v221
	s_nop 0
	v_cndmask_b32_e32 v57, v238, v57, vcc
	v_cmp_le_i32_e32 vcc, v14, v227
	v_or_b32_e32 v14, 0xf2, v221
	s_nop 0
	v_cndmask_b32_e32 v74, v238, v82, vcc
	v_cmp_le_i32_e32 vcc, v14, v227
	v_or_b32_e32 v14, 0xd3, v221
	s_nop 0
	v_cndmask_b32_e32 v58, v238, v58, vcc
	v_cmp_le_i32_e32 vcc, v14, v227
	v_or_b32_e32 v14, 0xf3, v221
	s_nop 0
	v_cndmask_b32_e32 v75, v238, v83, vcc
	v_cmp_le_i32_e32 vcc, v14, v227
	v_or_b32_e32 v14, 0xd8, v221
	v_max3_f32 v15, v15, v74, v75
	v_cndmask_b32_e32 v59, v238, v59, vcc
	v_cmp_le_i32_e32 vcc, v14, v227
	v_or_b32_e32 v14, 0xf8, v221
	v_max3_f32 v15, v15, v58, v59
	v_cndmask_b32_e32 v76, v238, v88, vcc
	v_cmp_le_i32_e32 vcc, v14, v227
	v_or_b32_e32 v14, 0xd9, v221
	s_nop 0
	v_cndmask_b32_e32 v60, v238, v60, vcc
	v_cmp_le_i32_e32 vcc, v14, v227
	v_or_b32_e32 v14, 0xf9, v221
	s_nop 0
	v_cndmask_b32_e32 v77, v238, v89, vcc
	v_cmp_le_i32_e32 vcc, v14, v227
	v_or_b32_e32 v14, 0xda, v221
	s_nop 0
	v_cndmask_b32_e32 v61, v238, v61, vcc
	v_cmp_le_i32_e32 vcc, v14, v227
	v_or_b32_e32 v14, 0xfa, v221
	s_nop 0
	v_cndmask_b32_e32 v78, v238, v90, vcc
	v_cmp_le_i32_e32 vcc, v14, v227
	v_or_b32_e32 v14, 0xdb, v221
	s_nop 0
	v_cndmask_b32_e32 v62, v238, v62, vcc
	v_cmp_le_i32_e32 vcc, v14, v227
	v_or_b32_e32 v14, 0xfb, v221
	s_nop 0
	v_cndmask_b32_e32 v79, v238, v91, vcc
	v_cmp_le_i32_e32 vcc, v14, v227
	v_max_f32_e32 v14, v64, v65
	v_max3_f32 v14, v14, v48, v50
	v_max3_f32 v14, v14, v51, v68
	v_max3_f32 v14, v14, v69, v52
	v_max3_f32 v14, v14, v53, v72
	v_max3_f32 v14, v14, v73, v56
	v_cndmask_b32_e32 v63, v238, v63, vcc
	v_max3_f32 v14, v14, v57, v76
	v_max3_f32 v15, v15, v78, v79
	v_max3_f32 v14, v14, v77, v60
	v_max3_f32 v15, v15, v62, v63
	v_max3_f32 v14, v14, v61, v15
	v_mov_b32_e32 v15, v14
	s_nop 1
	v_permlane32_swap_b32_e32 v14, v15
	v_max_f32_e32 v14, v14, v15
	v_cmp_lt_f32_e32 vcc, s36, v14
	s_cmp_lg_u64 vcc, 0
	s_cselect_b64 s[2:3], -1, 0
	s_cbranch_vccnz .LBB0_1395

.LBB0_1395:
	v_max_f32_e32 v14, 0, v14
	v_add_f32_e32 v15, v229, v14
	v_xor_b32_e32 v80, 0x80000000, v15
	v_exp_f32_e64 v15, -v14
	v_mov_b32_e32 v81, v80
	v_mov_b32_e32 v82, v80
	v_mov_b32_e32 v83, v80
	v_mov_b32_e32 v84, v80
	v_mov_b32_e32 v85, v80
	v_mov_b32_e32 v86, v80
	v_mov_b32_e32 v87, v80
	v_mov_b32_e32 v88, v80
	v_mov_b32_e32 v89, v80
	v_mov_b32_e32 v90, v80
	v_mov_b32_e32 v91, v80
	v_mov_b32_e32 v92, v80
	v_mov_b32_e32 v93, v80
	v_mov_b32_e32 v94, v80
	v_mov_b32_e32 v95, v80
	v_cmp_gt_u32_e32 vcc, 32, v217
	s_and_saveexec_b64 s[4:5], vcc
	ds_write_b32 v226, v15 offset:49152
	s_or_b64 exec, exec, s[4:5]
	v_sub_f32_e32 v79, v79, v14
	v_sub_f32_e32 v78, v78, v14
	v_sub_f32_e32 v77, v77, v14
	v_sub_f32_e32 v76, v76, v14
	v_sub_f32_e32 v75, v75, v14
	v_sub_f32_e32 v74, v74, v14
	v_sub_f32_e32 v73, v73, v14
	v_sub_f32_e32 v72, v72, v14
	v_sub_f32_e32 v71, v71, v14
	v_sub_f32_e32 v70, v70, v14
	v_sub_f32_e32 v69, v69, v14
	v_sub_f32_e32 v68, v68, v14
	v_sub_f32_e32 v67, v67, v14
	v_sub_f32_e32 v66, v66, v14
	v_sub_f32_e32 v65, v65, v14
	v_sub_f32_e32 v64, v64, v14
	v_sub_f32_e32 v63, v63, v14
	v_sub_f32_e32 v62, v62, v14
	v_sub_f32_e32 v61, v61, v14
	v_sub_f32_e32 v60, v60, v14
	v_sub_f32_e32 v59, v59, v14
	v_sub_f32_e32 v58, v58, v14
	v_sub_f32_e32 v57, v57, v14
	v_sub_f32_e32 v56, v56, v14
	v_sub_f32_e32 v55, v55, v14
	v_sub_f32_e32 v54, v54, v14
	v_sub_f32_e32 v53, v53, v14
	v_sub_f32_e32 v52, v52, v14
	v_sub_f32_e32 v51, v51, v14
	v_sub_f32_e32 v50, v50, v14
	v_sub_f32_e32 v49, v49, v14
	v_sub_f32_e32 v48, v48, v14
	v_mul_f32_e32 v0, v0, v15
	s_branch .LBB0_1383

.LBB0_1684:
	s_mov_b64 s[2:3], 0x6300000
	v_add_u32_e32 v130, s41, v133
	v_lshl_add_u32 v132, s14, 8, v130
	v_ashrrev_i32_e32 v133, 31, v132
	v_lshlrev_b64 v[132:133], 6, v[132:133]
	v_lshl_add_u64 v[142:143], s[4:5], 0, v[132:133]
	v_lshl_add_u64 v[132:133], v[142:143], 0, s[2:3]
	v_add_co_u32_e32 v204, vcc, 0x2000, v132
	s_nop 1
	v_addc_co_u32_e32 v205, vcc, 0, v133, vcc
	global_load_dwordx4 v[156:159], v[132:133], off sc1
	global_load_dwordx4 v[160:163], v[132:133], off offset:16 sc1
	global_load_dwordx4 v[164:167], v[132:133], off offset:32 sc1
	global_load_dwordx4 v[168:171], v[132:133], off offset:48 sc1
	global_load_dwordx4 v[172:175], v[132:133], off offset:1024 sc1
	global_load_dwordx4 v[176:179], v[132:133], off offset:1040 sc1
	global_load_dwordx4 v[180:183], v[132:133], off offset:1056 sc1
	global_load_dwordx4 v[184:187], v[132:133], off offset:1072 sc1
	global_load_dwordx4 v[188:191], v[132:133], off offset:2048 sc1
	global_load_dwordx4 v[192:195], v[132:133], off offset:2064 sc1
	global_load_dwordx4 v[196:199], v[132:133], off offset:2080 sc1
	global_load_dwordx4 v[200:203], v[132:133], off offset:2096 sc1
	s_waitcnt vmcnt(8)
	v_pk_add_f32 v[156:157], v[156:157], v[160:161]
	v_pk_add_f32 v[158:159], v[158:159], v[162:163]
	v_pk_add_f32 v[164:165], v[164:165], v[168:169]
	v_pk_add_f32 v[166:167], v[166:167], v[170:171]
	v_pk_add_f32 v[156:157], v[156:157], v[164:165]
	v_pk_add_f32 v[158:159], v[158:159], v[166:167]
	v_pk_add_f32 v[156:157], v[156:157], v[158:159]
	s_nop 0
	v_add_f32_e32 v206, v156, v157
	v_fmamk_f32 v206, v206, 0x3a800000, v231
	v_rsq_f32_e32 v206, v206
	global_load_dwordx4 v[156:159], v[132:133], off offset:3072 sc1
	global_load_dwordx4 v[160:163], v[132:133], off offset:3088 sc1
	global_load_dwordx4 v[164:167], v[132:133], off offset:3104 sc1
	global_load_dwordx4 v[168:171], v[132:133], off offset:3120 sc1
	s_waitcnt vmcnt(8)
	v_pk_add_f32 v[172:173], v[172:173], v[176:177]
	v_pk_add_f32 v[174:175], v[174:175], v[178:179]
	v_pk_add_f32 v[180:181], v[180:181], v[184:185]
	v_pk_add_f32 v[182:183], v[182:183], v[186:187]
	v_pk_add_f32 v[172:173], v[172:173], v[180:181]
	v_pk_add_f32 v[174:175], v[174:175], v[182:183]
	v_pk_add_f32 v[172:173], v[172:173], v[174:175]
	s_nop 0
	v_add_f32_e32 v207, v172, v173
	v_fmamk_f32 v207, v207, 0x3a800000, v231
	v_rsq_f32_e32 v207, v207
	global_load_dwordx4 v[172:175], v[204:205], off sc1
	global_load_dwordx4 v[176:179], v[204:205], off offset:16 sc1
	global_load_dwordx4 v[180:183], v[204:205], off offset:32 sc1
	global_load_dwordx4 v[184:187], v[204:205], off offset:48 sc1
	s_waitcnt vmcnt(8)
	v_pk_add_f32 v[188:189], v[188:189], v[192:193]
	v_pk_add_f32 v[190:191], v[190:191], v[194:195]
	v_pk_add_f32 v[196:197], v[196:197], v[200:201]
	v_pk_add_f32 v[198:199], v[198:199], v[202:203]
	v_pk_add_f32 v[188:189], v[188:189], v[196:197]
	v_pk_add_f32 v[190:191], v[190:191], v[198:199]
	v_pk_add_f32 v[188:189], v[188:189], v[190:191]
	s_nop 0
	v_add_f32_e32 v208, v188, v189
	v_fmamk_f32 v208, v208, 0x3a800000, v231
	v_rsq_f32_e32 v208, v208
	global_load_dwordx4 v[188:191], v[204:205], off offset:1024 sc1
	global_load_dwordx4 v[192:195], v[204:205], off offset:1040 sc1
	global_load_dwordx4 v[196:199], v[204:205], off offset:1056 sc1
	global_load_dwordx4 v[200:203], v[204:205], off offset:1072 sc1
	s_waitcnt vmcnt(8)
	v_pk_add_f32 v[156:157], v[156:157], v[160:161]
	v_pk_add_f32 v[158:159], v[158:159], v[162:163]
	v_pk_add_f32 v[164:165], v[164:165], v[168:169]
	v_pk_add_f32 v[166:167], v[166:167], v[170:171]
	v_pk_add_f32 v[156:157], v[156:157], v[164:165]
	v_pk_add_f32 v[158:159], v[158:159], v[166:167]
	v_pk_add_f32 v[156:157], v[156:157], v[158:159]
	s_nop 0
	v_add_f32_e32 v209, v156, v157
	v_fmamk_f32 v209, v209, 0x3a800000, v231
	v_rsq_f32_e32 v209, v209
	global_load_dwordx4 v[156:159], v[204:205], off offset:2048 sc1
	global_load_dwordx4 v[160:163], v[204:205], off offset:2064 sc1
	global_load_dwordx4 v[164:167], v[204:205], off offset:2080 sc1
	global_load_dwordx4 v[168:171], v[204:205], off offset:2096 sc1
	s_waitcnt vmcnt(8)
	v_pk_add_f32 v[172:173], v[172:173], v[176:177]
	v_pk_add_f32 v[174:175], v[174:175], v[178:179]
	v_pk_add_f32 v[180:181], v[180:181], v[184:185]
	v_pk_add_f32 v[182:183], v[182:183], v[186:187]
	v_pk_add_f32 v[172:173], v[172:173], v[180:181]
	v_pk_add_f32 v[174:175], v[174:175], v[182:183]
	v_pk_add_f32 v[172:173], v[172:173], v[174:175]
	s_nop 0
	v_add_f32_e32 v210, v172, v173
	v_fmamk_f32 v210, v210, 0x3a800000, v231
	v_rsq_f32_e32 v210, v210
	global_load_dwordx4 v[172:175], v[204:205], off offset:3072 sc1
	global_load_dwordx4 v[176:179], v[204:205], off offset:3088 sc1
	global_load_dwordx4 v[180:183], v[204:205], off offset:3104 sc1
	global_load_dwordx4 v[184:187], v[204:205], off offset:3120 sc1
	s_waitcnt vmcnt(8)
	v_pk_add_f32 v[188:189], v[188:189], v[192:193]
	v_pk_add_f32 v[190:191], v[190:191], v[194:195]
	v_pk_add_f32 v[196:197], v[196:197], v[200:201]
	v_pk_add_f32 v[198:199], v[198:199], v[202:203]
	v_pk_add_f32 v[188:189], v[188:189], v[196:197]
	v_pk_add_f32 v[190:191], v[190:191], v[198:199]
	v_pk_add_f32 v[188:189], v[188:189], v[190:191]
	s_nop 0
	v_add_f32_e32 v211, v188, v189
	v_fmamk_f32 v211, v211, 0x3a800000, v231
	v_rsq_f32_e32 v211, v211
	s_waitcnt vmcnt(4)
	v_pk_add_f32 v[156:157], v[156:157], v[160:161]
	v_pk_add_f32 v[158:159], v[158:159], v[162:163]
	v_pk_add_f32 v[164:165], v[164:165], v[168:169]
	v_pk_add_f32 v[166:167], v[166:167], v[170:171]
	v_pk_add_f32 v[156:157], v[156:157], v[164:165]
	v_pk_add_f32 v[158:159], v[158:159], v[166:167]
	v_pk_add_f32 v[156:157], v[156:157], v[158:159]
	s_nop 0
	v_add_f32_e32 v212, v156, v157
	v_fmamk_f32 v212, v212, 0x3a800000, v231
	v_rsq_f32_e32 v212, v212
	s_waitcnt vmcnt(0)
	v_pk_add_f32 v[172:173], v[172:173], v[176:177]
	v_pk_add_f32 v[174:175], v[174:175], v[178:179]
	v_pk_add_f32 v[180:181], v[180:181], v[184:185]
	v_pk_add_f32 v[182:183], v[182:183], v[186:187]
	v_pk_add_f32 v[172:173], v[172:173], v[180:181]
	v_pk_add_f32 v[174:175], v[174:175], v[182:183]
	v_pk_add_f32 v[172:173], v[172:173], v[174:175]
	s_nop 0
	v_add_f32_e32 v213, v172, v173
	v_fmamk_f32 v213, v213, 0x3a800000, v231
	v_rsq_f32_e32 v213, v213
	s_mov_b32 s2, 0xff61b1e6
	s_cmpk_lt_u32 s17, 0x100
	s_cbranch_scc0 .Lepi_lead_r6
	s_barrier
.Lepi_lead_r6:
	v_mov_b32_e32 v0, v206
	v_pk_mul_f32 v[128:129], v[128:129], v[0:1] op_sel_hi:[1,0]
	v_pk_mul_f32 v[124:125], v[124:125], v[0:1] op_sel_hi:[1,0]
	v_pk_mul_f32 v[126:127], v[126:127], v[0:1] op_sel_hi:[1,0]
	v_pk_mul_f32 v[122:123], v[122:123], v[0:1] op_sel_hi:[1,0]
	v_pk_mul_f32 v[120:121], v[120:121], v[0:1] op_sel_hi:[1,0]
	v_pk_mul_f32 v[118:119], v[118:119], v[0:1] op_sel_hi:[1,0]
	v_pk_mul_f32 v[116:117], v[116:117], v[0:1] op_sel_hi:[1,0]
	v_pk_mul_f32 v[114:115], v[114:115], v[0:1] op_sel_hi:[1,0]
	v_max_f32_e32 v0, v128, v129
	v_max_f32_e32 v134, v124, v125
	v_max_f32_e32 v135, v120, v121
	v_max_f32_e32 v136, v116, v117
	v_max3_f32 v0, v126, v127, v0
	v_max3_f32 v134, v122, v123, v134
	v_max3_f32 v135, v118, v119, v135
	v_max3_f32 v136, v114, v115, v136
	v_max3_f32 v0, v0, s2, v134
	v_max3_f32 v0, v0, v135, v136
	ds_swizzle_b32 v134, v0 offset:swizzle(SWAP,16)
	s_lshl_b32 s2, s16, 2
	s_add_i32 s8, s2, 0
	v_cmp_eq_u32_e64 s[2:3], 0, v131
	s_add_i32 s9, s8, 0x20000
	s_waitcnt lgkmcnt(0)
	v_max_f32_e32 v134, v134, v134
	v_max_f32_e32 v0, v0, v134
	v_mov_b32_e32 v134, v0
	s_nop 1
	v_permlane32_swap_b32_e32 v0, v134
	s_and_saveexec_b64 s[6:7], s[2:3]
	v_max_f32_e32 v0, v0, v0
	v_max_f32_e32 v134, v134, v134
	v_lshl_add_u32 v135, v130, 4, s9
	v_max_f32_e32 v0, v0, v134
	ds_write_b32 v135, v0
	s_or_b64 exec, exec, s[6:7]
	s_mov_b32 s6, 0xff61b1e6
	v_add_u32_e32 v140, 16, v130
	v_mov_b32_e32 v0, v207
	v_pk_mul_f32 v[112:113], v[112:113], v[0:1] op_sel_hi:[1,0]
	v_pk_mul_f32 v[108:109], v[108:109], v[0:1] op_sel_hi:[1,0]
	v_pk_mul_f32 v[110:111], v[110:111], v[0:1] op_sel_hi:[1,0]
	v_pk_mul_f32 v[106:107], v[106:107], v[0:1] op_sel_hi:[1,0]
	v_pk_mul_f32 v[104:105], v[104:105], v[0:1] op_sel_hi:[1,0]
	v_pk_mul_f32 v[102:103], v[102:103], v[0:1] op_sel_hi:[1,0]
	v_pk_mul_f32 v[100:101], v[100:101], v[0:1] op_sel_hi:[1,0]
	v_pk_mul_f32 v[98:99], v[98:99], v[0:1] op_sel_hi:[1,0]
	v_max_f32_e32 v0, v112, v113
	v_max_f32_e32 v134, v108, v109
	v_max_f32_e32 v135, v104, v105
	v_max_f32_e32 v136, v100, v101
	v_max3_f32 v0, v110, v111, v0
	v_max3_f32 v134, v106, v107, v134
	v_max3_f32 v135, v102, v103, v135
	v_max3_f32 v136, v98, v99, v136
	v_max3_f32 v0, v0, s6, v134
	v_max3_f32 v0, v0, v135, v136
	ds_swizzle_b32 v134, v0 offset:swizzle(SWAP,16)
	s_waitcnt lgkmcnt(0)
	v_max_f32_e32 v134, v134, v134
	v_max_f32_e32 v0, v0, v134
	v_mov_b32_e32 v134, v0
	s_nop 1
	v_permlane32_swap_b32_e32 v0, v134
	s_and_saveexec_b64 s[6:7], s[2:3]
	v_max_f32_e32 v0, v0, v0
	v_max_f32_e32 v134, v134, v134
	v_lshl_add_u32 v135, v140, 4, s9
	v_max_f32_e32 v0, v0, v134
	ds_write_b32 v135, v0
	s_or_b64 exec, exec, s[6:7]
	s_mov_b32 s6, 0xff61b1e6
	v_add_u32_e32 v141, 32, v130
	v_mov_b32_e32 v0, v208
	v_pk_mul_f32 v[96:97], v[96:97], v[0:1] op_sel_hi:[1,0]
	v_pk_mul_f32 v[92:93], v[92:93], v[0:1] op_sel_hi:[1,0]
	v_pk_mul_f32 v[94:95], v[94:95], v[0:1] op_sel_hi:[1,0]
	v_pk_mul_f32 v[90:91], v[90:91], v[0:1] op_sel_hi:[1,0]
	v_pk_mul_f32 v[88:89], v[88:89], v[0:1] op_sel_hi:[1,0]
	v_pk_mul_f32 v[86:87], v[86:87], v[0:1] op_sel_hi:[1,0]
	v_pk_mul_f32 v[84:85], v[84:85], v[0:1] op_sel_hi:[1,0]
	v_pk_mul_f32 v[82:83], v[82:83], v[0:1] op_sel_hi:[1,0]
	v_max_f32_e32 v0, v96, v97
	v_max_f32_e32 v134, v92, v93
	v_max_f32_e32 v135, v88, v89
	v_max_f32_e32 v136, v84, v85
	v_max3_f32 v0, v94, v95, v0
	v_max3_f32 v134, v90, v91, v134
	v_max3_f32 v135, v86, v87, v135
	v_max3_f32 v136, v82, v83, v136
	v_max3_f32 v0, v0, s6, v134
	v_max3_f32 v0, v0, v135, v136
	ds_swizzle_b32 v134, v0 offset:swizzle(SWAP,16)
	s_waitcnt lgkmcnt(0)
	v_max_f32_e32 v134, v134, v134
	v_max_f32_e32 v0, v0, v134
	v_mov_b32_e32 v134, v0
	s_nop 1
	v_permlane32_swap_b32_e32 v0, v134
	s_and_saveexec_b64 s[6:7], s[2:3]
	v_max_f32_e32 v0, v0, v0
	v_max_f32_e32 v134, v134, v134
	v_lshl_add_u32 v135, v141, 4, s9
	v_max_f32_e32 v0, v0, v134
	ds_write_b32 v135, v0
	s_or_b64 exec, exec, s[6:7]
	s_mov_b32 s6, 0xff61b1e6
	v_add_u32_e32 v142, 48, v130
	v_mov_b32_e32 v0, v209
	v_pk_mul_f32 v[80:81], v[80:81], v[0:1] op_sel_hi:[1,0]
	v_pk_mul_f32 v[76:77], v[76:77], v[0:1] op_sel_hi:[1,0]
	v_pk_mul_f32 v[78:79], v[78:79], v[0:1] op_sel_hi:[1,0]
	v_pk_mul_f32 v[74:75], v[74:75], v[0:1] op_sel_hi:[1,0]
	v_pk_mul_f32 v[72:73], v[72:73], v[0:1] op_sel_hi:[1,0]
	v_pk_mul_f32 v[70:71], v[70:71], v[0:1] op_sel_hi:[1,0]
	v_pk_mul_f32 v[68:69], v[68:69], v[0:1] op_sel_hi:[1,0]
	v_pk_mul_f32 v[66:67], v[66:67], v[0:1] op_sel_hi:[1,0]
	v_max_f32_e32 v0, v80, v81
	v_max_f32_e32 v134, v76, v77
	v_max_f32_e32 v135, v72, v73
	v_max_f32_e32 v136, v68, v69
	v_max3_f32 v0, v78, v79, v0
	v_max3_f32 v134, v74, v75, v134
	v_max3_f32 v135, v70, v71, v135
	v_max3_f32 v136, v66, v67, v136
	v_max3_f32 v0, v0, s6, v134
	v_max3_f32 v0, v0, v135, v136
	ds_swizzle_b32 v134, v0 offset:swizzle(SWAP,16)
	s_waitcnt lgkmcnt(0)
	v_max_f32_e32 v134, v134, v134
	v_max_f32_e32 v0, v0, v134
	v_mov_b32_e32 v134, v0
	s_nop 1
	v_permlane32_swap_b32_e32 v0, v134
	s_and_saveexec_b64 s[6:7], s[2:3]
	v_max_f32_e32 v0, v0, v0
	v_max_f32_e32 v134, v134, v134
	v_lshl_add_u32 v135, v142, 4, s9
	v_max_f32_e32 v0, v0, v134
	ds_write_b32 v135, v0
	s_or_b64 exec, exec, s[6:7]
	s_mov_b32 s6, 0xff61b1e6
	v_add_u32_e32 v0, 0x80, v130
	v_mov_b32_e32 v134, v210
	v_pk_mul_f32 v[64:65], v[64:65], v[134:135] op_sel_hi:[1,0]
	v_pk_mul_f32 v[62:63], v[62:63], v[134:135] op_sel_hi:[1,0]
	v_max_f32_e32 v135, v64, v65
	v_max3_f32 v135, v62, v63, v135
	v_pk_mul_f32 v[60:61], v[60:61], v[134:135] op_sel_hi:[1,0]
	v_pk_mul_f32 v[58:59], v[58:59], v[134:135] op_sel_hi:[1,0]
	v_max_f32_e32 v136, v60, v61
	v_max3_f32 v136, v58, v59, v136
	v_max3_f32 v135, v135, s6, v136
	v_pk_mul_f32 v[56:57], v[56:57], v[134:135] op_sel_hi:[1,0]
	v_pk_mul_f32 v[52:53], v[52:53], v[134:135] op_sel_hi:[1,0]
	v_pk_mul_f32 v[54:55], v[54:55], v[134:135] op_sel_hi:[1,0]
	v_max_f32_e32 v136, v56, v57
	v_pk_mul_f32 v[50:51], v[50:51], v[134:135] op_sel_hi:[1,0]
	v_max_f32_e32 v134, v52, v53
	v_max3_f32 v136, v54, v55, v136
	v_max3_f32 v134, v50, v51, v134
	v_max3_f32 v134, v135, v136, v134
	ds_swizzle_b32 v135, v134 offset:swizzle(SWAP,16)
	s_waitcnt lgkmcnt(0)
	v_max_f32_e32 v135, v135, v135
	v_max_f32_e32 v134, v134, v135
	v_mov_b32_e32 v135, v134
	s_nop 1
	v_permlane32_swap_b32_e32 v134, v135
	s_and_saveexec_b64 s[6:7], s[2:3]
	v_max_f32_e32 v134, v134, v134
	v_max_f32_e32 v135, v135, v135
	v_lshl_add_u32 v136, v0, 4, s9
	v_max_f32_e32 v134, v134, v135
	ds_write_b32 v136, v134
	s_or_b64 exec, exec, s[6:7]
	s_mov_b32 s6, 0xff61b1e6
	v_add_u32_e32 v143, 0x90, v130
	v_mov_b32_e32 v134, v211
	v_pk_mul_f32 v[48:49], v[48:49], v[134:135] op_sel_hi:[1,0]
	v_pk_mul_f32 v[46:47], v[46:47], v[134:135] op_sel_hi:[1,0]
	v_max_f32_e32 v135, v48, v49
	v_max3_f32 v135, v46, v47, v135
	v_pk_mul_f32 v[44:45], v[44:45], v[134:135] op_sel_hi:[1,0]
	v_pk_mul_f32 v[42:43], v[42:43], v[134:135] op_sel_hi:[1,0]
	v_max_f32_e32 v136, v44, v45
	v_max3_f32 v136, v42, v43, v136
	v_max3_f32 v135, v135, s6, v136
	v_pk_mul_f32 v[40:41], v[40:41], v[134:135] op_sel_hi:[1,0]
	v_pk_mul_f32 v[36:37], v[36:37], v[134:135] op_sel_hi:[1,0]
	v_pk_mul_f32 v[38:39], v[38:39], v[134:135] op_sel_hi:[1,0]
	v_max_f32_e32 v136, v40, v41
	v_pk_mul_f32 v[34:35], v[34:35], v[134:135] op_sel_hi:[1,0]
	v_max_f32_e32 v134, v36, v37
	v_max3_f32 v136, v38, v39, v136
	v_max3_f32 v134, v34, v35, v134
	v_max3_f32 v134, v135, v136, v134
	ds_swizzle_b32 v135, v134 offset:swizzle(SWAP,16)
	s_waitcnt lgkmcnt(0)
	v_max_f32_e32 v135, v135, v135
	v_max_f32_e32 v134, v134, v135
	v_mov_b32_e32 v135, v134
	s_nop 1
	v_permlane32_swap_b32_e32 v134, v135
	s_and_saveexec_b64 s[6:7], s[2:3]
	v_max_f32_e32 v134, v134, v134
	v_max_f32_e32 v135, v135, v135
	v_lshl_add_u32 v136, v143, 4, s9
	v_max_f32_e32 v134, v134, v135
	ds_write_b32 v136, v134
	s_or_b64 exec, exec, s[6:7]
	s_mov_b32 s6, 0xff61b1e6
	v_add_u32_e32 v144, 0xa0, v130
	v_mov_b32_e32 v134, v212
	v_pk_mul_f32 v[32:33], v[32:33], v[134:135] op_sel_hi:[1,0]
	v_pk_mul_f32 v[30:31], v[30:31], v[134:135] op_sel_hi:[1,0]
	v_max_f32_e32 v135, v32, v33
	v_max3_f32 v135, v30, v31, v135
	v_pk_mul_f32 v[28:29], v[28:29], v[134:135] op_sel_hi:[1,0]
	v_pk_mul_f32 v[26:27], v[26:27], v[134:135] op_sel_hi:[1,0]
	v_max_f32_e32 v136, v28, v29
	v_max3_f32 v136, v26, v27, v136
	v_max3_f32 v135, v135, s6, v136
	v_pk_mul_f32 v[24:25], v[24:25], v[134:135] op_sel_hi:[1,0]
	v_pk_mul_f32 v[20:21], v[20:21], v[134:135] op_sel_hi:[1,0]
	v_pk_mul_f32 v[22:23], v[22:23], v[134:135] op_sel_hi:[1,0]
	v_max_f32_e32 v136, v24, v25
	v_pk_mul_f32 v[18:19], v[18:19], v[134:135] op_sel_hi:[1,0]
	v_max_f32_e32 v134, v20, v21
	v_max3_f32 v136, v22, v23, v136
	v_max3_f32 v134, v18, v19, v134
	v_max3_f32 v134, v135, v136, v134
	ds_swizzle_b32 v135, v134 offset:swizzle(SWAP,16)
	s_waitcnt lgkmcnt(0)
	v_max_f32_e32 v135, v135, v135
	v_max_f32_e32 v134, v134, v135
	v_mov_b32_e32 v135, v134
	s_nop 1
	v_permlane32_swap_b32_e32 v134, v135
	s_and_saveexec_b64 s[6:7], s[2:3]
	v_max_f32_e32 v134, v134, v134
	v_max_f32_e32 v135, v135, v135
	v_lshl_add_u32 v136, v144, 4, s9
	v_max_f32_e32 v134, v134, v135
	ds_write_b32 v136, v134
	s_or_b64 exec, exec, s[6:7]
	s_mov_b64 s[6:7], 0x2c00
	v_lshl_add_u64 v[150:151], v[132:133], 0, s[6:7]
	v_add_co_u32_e32 v132, vcc, 0x2000, v132
	s_mov_b32 s6, 0xff61b1e6
	s_nop 0
	v_addc_co_u32_e32 v133, vcc, 0, v133, vcc
	v_add_u32_e32 v145, 0xb0, v130
	v_mov_b32_e32 v154, v132
	v_mov_b32_e32 v150, v133
	v_mov_b32_e32 v134, v213
	v_pk_mul_f32 v[16:17], v[16:17], v[134:135] op_sel_hi:[1,0]
	v_pk_mul_f32 v[14:15], v[14:15], v[134:135] op_sel_hi:[1,0]
	v_max_f32_e32 v132, v16, v17
	v_max3_f32 v135, v14, v15, v132
	v_pk_mul_f32 v[132:133], v[12:13], v[134:135] op_sel_hi:[1,0]
	v_pk_mul_f32 v[12:13], v[10:11], v[134:135] op_sel_hi:[1,0]
	v_max_f32_e32 v10, v132, v133
	v_max3_f32 v10, v12, v13, v10
	v_pk_mul_f32 v[136:137], v[8:9], v[134:135] op_sel_hi:[1,0]
	v_pk_mul_f32 v[138:139], v[4:5], v[134:135] op_sel_hi:[1,0]
	v_max3_f32 v10, v135, s6, v10
	v_pk_mul_f32 v[8:9], v[6:7], v[134:135] op_sel_hi:[1,0]
	v_max_f32_e32 v6, v136, v137
	v_pk_mul_f32 v[134:135], v[2:3], v[134:135] op_sel_hi:[1,0]
	v_max_f32_e32 v2, v138, v139
	v_max3_f32 v6, v8, v9, v6
	v_max3_f32 v2, v134, v135, v2
	v_max3_f32 v2, v10, v6, v2
	ds_swizzle_b32 v3, v2 offset:swizzle(SWAP,16)
	s_waitcnt lgkmcnt(0)
	v_max_f32_e32 v3, v3, v3
	v_max_f32_e32 v2, v2, v3
	v_mov_b32_e32 v3, v2
	s_nop 1
	v_permlane32_swap_b32_e32 v2, v3
	s_and_saveexec_b64 s[6:7], s[2:3]
	v_max_f32_e32 v2, v2, v2
	v_max_f32_e32 v3, v3, v3
	v_lshl_add_u32 v4, v145, 4, s9
	v_max_f32_e32 v2, v2, v3
	ds_write_b32 v4, v2
	s_or_b64 exec, exec, s[6:7]
	v_lshl_add_u32 v2, v130, 4, 0
	s_waitcnt lgkmcnt(0)
	s_barrier
	v_add_u32_e32 v2, 0x20000, v2
	ds_read_b128 v[4:7], v2
	s_add_i32 s8, s8, 0x21000
	s_waitcnt lgkmcnt(0)
	v_max_f32_e32 v3, v7, v7
	v_max_f32_e32 v6, v6, v6
	v_max_f32_e32 v3, v6, v3
	v_max3_f32 v3, v4, v5, v3
	v_sub_f32_e32 v4, v129, v3
	v_sub_f32_e32 v5, v128, v3
	v_sub_f32_e32 v6, v127, v3
	v_sub_f32_e32 v7, v126, v3
	v_exp_f32_e32 v126, v7
	v_exp_f32_e32 v127, v6
	v_exp_f32_e32 v128, v5
	v_exp_f32_e32 v129, v4
	v_sub_f32_e32 v6, v125, v3
	v_sub_f32_e32 v7, v124, v3
	v_sub_f32_e32 v10, v123, v3
	v_sub_f32_e32 v11, v122, v3
	v_exp_f32_e32 v122, v11
	v_exp_f32_e32 v123, v10
	v_exp_f32_e32 v124, v7
	v_exp_f32_e32 v125, v6
	v_sub_f32_e32 v7, v121, v3
	v_sub_f32_e32 v10, v120, v3
	v_sub_f32_e32 v11, v119, v3
	v_sub_f32_e32 v118, v118, v3
	v_exp_f32_e32 v118, v118
	v_exp_f32_e32 v119, v11
	v_exp_f32_e32 v120, v10
	v_exp_f32_e32 v121, v7
	v_add_f32_e32 v4, v126, v127
	v_add_f32_e32 v5, v128, v129
	v_sub_f32_e32 v7, v117, v3
	v_sub_f32_e32 v10, v116, v3
	v_sub_f32_e32 v11, v115, v3
	v_sub_f32_e32 v3, v114, v3
	v_add_f32_e32 v4, v4, v5
	v_add_f32_e32 v5, v122, v123
	v_add_f32_e32 v6, v124, v125
	v_exp_f32_e32 v114, v3
	v_exp_f32_e32 v115, v11
	v_exp_f32_e32 v116, v10
	v_exp_f32_e32 v117, v7
	v_add_f32_e32 v4, 0, v4
	v_add_f32_e32 v5, v5, v6
	v_add_f32_e32 v4, v5, v4
	v_add_f32_e32 v5, v118, v119
	v_add_f32_e32 v6, v120, v121
	v_add_f32_e32 v3, v5, v6
	v_add_f32_e32 v3, v3, v4
	v_add_f32_e32 v4, v114, v115
	v_add_f32_e32 v5, v116, v117
	v_add_f32_e32 v4, v4, v5
	v_add_f32_e32 v3, v4, v3
	ds_swizzle_b32 v4, v3 offset:swizzle(SWAP,16)
	v_lshlrev_b32_e32 v5, 2, v130
	v_lshl_add_u32 v146, v5, 2, s8
	s_waitcnt lgkmcnt(0)
	v_add_f32_e32 v3, v3, v4
	v_mov_b32_e32 v4, v3
	s_nop 1
	v_permlane32_swap_b32_e32 v3, v4
	s_and_saveexec_b64 s[6:7], s[2:3]
	v_add_f32_e32 v3, v3, v4
	ds_write_b32 v146, v3
	s_or_b64 exec, exec, s[6:7]
	ds_read_b128 v[4:7], v2 offset:256
	s_waitcnt lgkmcnt(0)
	v_max_f32_e32 v3, v7, v7
	v_max_f32_e32 v6, v6, v6
	v_max_f32_e32 v3, v6, v3
	v_max3_f32 v3, v4, v5, v3
	v_sub_f32_e32 v4, v113, v3
	v_sub_f32_e32 v5, v112, v3
	v_sub_f32_e32 v6, v111, v3
	v_sub_f32_e32 v7, v110, v3
	v_exp_f32_e32 v110, v7
	v_exp_f32_e32 v111, v6
	v_exp_f32_e32 v112, v5
	v_exp_f32_e32 v113, v4
	v_sub_f32_e32 v6, v109, v3
	v_sub_f32_e32 v7, v108, v3
	v_sub_f32_e32 v10, v107, v3
	v_sub_f32_e32 v11, v106, v3
	v_exp_f32_e32 v106, v11
	v_exp_f32_e32 v107, v10
	v_exp_f32_e32 v108, v7
	v_exp_f32_e32 v109, v6
	v_sub_f32_e32 v7, v105, v3
	v_sub_f32_e32 v10, v104, v3
	v_sub_f32_e32 v11, v103, v3
	v_sub_f32_e32 v102, v102, v3
	v_exp_f32_e32 v102, v102
	v_exp_f32_e32 v103, v11
	v_exp_f32_e32 v104, v10
	v_exp_f32_e32 v105, v7
	v_add_f32_e32 v4, v110, v111
	v_add_f32_e32 v5, v112, v113
	v_sub_f32_e32 v7, v101, v3
	v_sub_f32_e32 v10, v100, v3
	v_sub_f32_e32 v11, v99, v3
	v_sub_f32_e32 v3, v98, v3
	v_add_f32_e32 v4, v4, v5
	v_add_f32_e32 v5, v106, v107
	v_add_f32_e32 v6, v108, v109
	v_exp_f32_e32 v98, v3
	v_exp_f32_e32 v99, v11
	v_exp_f32_e32 v100, v10
	v_exp_f32_e32 v101, v7
	v_add_f32_e32 v4, 0, v4
	v_add_f32_e32 v5, v5, v6
	v_add_f32_e32 v4, v5, v4
	v_add_f32_e32 v5, v102, v103
	v_add_f32_e32 v6, v104, v105
	v_add_f32_e32 v3, v5, v6
	v_add_f32_e32 v3, v3, v4
	v_add_f32_e32 v4, v98, v99
	v_add_f32_e32 v5, v100, v101
	v_add_f32_e32 v4, v4, v5
	v_add_f32_e32 v3, v4, v3
	ds_swizzle_b32 v4, v3 offset:swizzle(SWAP,16)
	s_waitcnt lgkmcnt(0)
	v_add_f32_e32 v3, v3, v4
	v_mov_b32_e32 v4, v3
	s_nop 1
	v_permlane32_swap_b32_e32 v3, v4
	s_and_saveexec_b64 s[6:7], s[2:3]
	v_add_f32_e32 v3, v3, v4
	ds_write_b32 v146, v3 offset:256
	s_or_b64 exec, exec, s[6:7]
	v_mad_u64_u32 v[4:5], s[6:7], v130, 3, v[0:1]
	v_lshl_add_u32 v3, v4, 2, 0
	v_add_u32_e32 v3, 0x20000, v3
	ds_read_b128 v[4:7], v3
	s_waitcnt lgkmcnt(0)
	v_max_f32_e32 v3, v7, v7
	v_max_f32_e32 v6, v6, v6
	v_max_f32_e32 v3, v6, v3
	v_max3_f32 v3, v4, v5, v3
	v_sub_f32_e32 v4, v97, v3
	v_sub_f32_e32 v5, v96, v3
	v_sub_f32_e32 v6, v95, v3
	v_sub_f32_e32 v7, v94, v3
	v_exp_f32_e32 v94, v7
	v_exp_f32_e32 v95, v6
	v_exp_f32_e32 v96, v5
	v_exp_f32_e32 v97, v4
	v_sub_f32_e32 v6, v93, v3
	v_sub_f32_e32 v7, v92, v3
	v_sub_f32_e32 v10, v91, v3
	v_sub_f32_e32 v11, v90, v3
	v_exp_f32_e32 v90, v11
	v_exp_f32_e32 v91, v10
	v_exp_f32_e32 v92, v7
	v_exp_f32_e32 v93, v6
	v_sub_f32_e32 v7, v89, v3
	v_sub_f32_e32 v10, v88, v3
	v_sub_f32_e32 v11, v87, v3
	v_sub_f32_e32 v86, v86, v3
	v_exp_f32_e32 v86, v86
	v_exp_f32_e32 v87, v11
	v_exp_f32_e32 v88, v10
	v_exp_f32_e32 v89, v7
	v_add_f32_e32 v4, v94, v95
	v_add_f32_e32 v5, v96, v97
	v_sub_f32_e32 v7, v85, v3
	v_sub_f32_e32 v10, v84, v3
	v_sub_f32_e32 v11, v83, v3
	v_sub_f32_e32 v3, v82, v3
	v_add_f32_e32 v4, v4, v5
	v_add_f32_e32 v5, v90, v91
	v_add_f32_e32 v6, v92, v93
	v_exp_f32_e32 v82, v3
	v_exp_f32_e32 v83, v11
	v_exp_f32_e32 v84, v10
	v_exp_f32_e32 v85, v7
	v_add_f32_e32 v4, 0, v4
	v_add_f32_e32 v5, v5, v6
	v_add_f32_e32 v4, v5, v4
	v_add_f32_e32 v5, v86, v87
	v_add_f32_e32 v6, v88, v89
	v_add_f32_e32 v3, v5, v6
	v_add_f32_e32 v3, v3, v4
	v_add_f32_e32 v4, v82, v83
	v_add_f32_e32 v5, v84, v85
	v_add_f32_e32 v4, v4, v5
	v_add_f32_e32 v3, v4, v3
	ds_swizzle_b32 v4, v3 offset:swizzle(SWAP,16)
	s_waitcnt lgkmcnt(0)
	v_add_f32_e32 v3, v3, v4
	v_mov_b32_e32 v4, v3
	s_nop 1
	v_permlane32_swap_b32_e32 v3, v4
	s_and_saveexec_b64 s[6:7], s[2:3]
	v_add_f32_e32 v3, v3, v4
	ds_write_b32 v146, v3 offset:512
	s_or_b64 exec, exec, s[6:7]
	ds_read_b128 v[4:7], v2 offset:768
	s_waitcnt lgkmcnt(0)
	v_max_f32_e32 v3, v7, v7
	v_max_f32_e32 v6, v6, v6
	v_max_f32_e32 v3, v6, v3
	v_max3_f32 v3, v4, v5, v3
	v_sub_f32_e32 v4, v81, v3
	v_sub_f32_e32 v5, v80, v3
	v_sub_f32_e32 v6, v79, v3
	v_sub_f32_e32 v7, v78, v3
	v_exp_f32_e32 v78, v7
	v_exp_f32_e32 v79, v6
	v_exp_f32_e32 v80, v5
	v_exp_f32_e32 v81, v4
	v_sub_f32_e32 v6, v77, v3
	v_sub_f32_e32 v7, v76, v3
	v_sub_f32_e32 v10, v75, v3
	v_sub_f32_e32 v11, v74, v3
	v_exp_f32_e32 v74, v11
	v_exp_f32_e32 v75, v10
	v_exp_f32_e32 v76, v7
	v_exp_f32_e32 v77, v6
	v_sub_f32_e32 v7, v73, v3
	v_sub_f32_e32 v10, v72, v3
	v_sub_f32_e32 v11, v71, v3
	v_sub_f32_e32 v70, v70, v3
	v_exp_f32_e32 v70, v70
	v_exp_f32_e32 v71, v11
	v_exp_f32_e32 v72, v10
	v_exp_f32_e32 v73, v7
	v_add_f32_e32 v4, v78, v79
	v_add_f32_e32 v5, v80, v81
	v_sub_f32_e32 v7, v69, v3
	v_sub_f32_e32 v10, v68, v3
	v_sub_f32_e32 v11, v67, v3
	v_sub_f32_e32 v3, v66, v3
	v_add_f32_e32 v4, v4, v5
	v_add_f32_e32 v5, v74, v75
	v_add_f32_e32 v6, v76, v77
	v_exp_f32_e32 v66, v3
	v_exp_f32_e32 v67, v11
	v_exp_f32_e32 v68, v10
	v_exp_f32_e32 v69, v7
	v_add_f32_e32 v4, 0, v4
	v_add_f32_e32 v5, v5, v6
	v_add_f32_e32 v4, v5, v4
	v_add_f32_e32 v5, v70, v71
	v_add_f32_e32 v6, v72, v73
	v_add_f32_e32 v3, v5, v6
	v_add_f32_e32 v3, v3, v4
	v_add_f32_e32 v4, v66, v67
	v_add_f32_e32 v5, v68, v69
	v_add_f32_e32 v4, v4, v5
	v_add_f32_e32 v3, v4, v3
	ds_swizzle_b32 v4, v3 offset:swizzle(SWAP,16)
	s_waitcnt lgkmcnt(0)
	v_add_f32_e32 v3, v3, v4
	v_mov_b32_e32 v4, v3
	s_nop 1
	v_permlane32_swap_b32_e32 v3, v4
	s_and_saveexec_b64 s[6:7], s[2:3]
	v_add_f32_e32 v3, v3, v4
	ds_write_b32 v146, v3 offset:768
	s_or_b64 exec, exec, s[6:7]
	ds_read_b128 v[4:7], v2 offset:2048
	s_waitcnt lgkmcnt(0)
	v_max_f32_e32 v3, v7, v7
	v_max_f32_e32 v6, v6, v6
	v_max_f32_e32 v3, v6, v3
	v_max3_f32 v3, v4, v5, v3
	v_sub_f32_e32 v4, v65, v3
	v_sub_f32_e32 v5, v64, v3
	v_sub_f32_e32 v6, v63, v3
	v_sub_f32_e32 v7, v62, v3
	v_exp_f32_e32 v62, v7
	v_exp_f32_e32 v63, v6
	v_exp_f32_e32 v64, v5
	v_exp_f32_e32 v65, v4
	v_sub_f32_e32 v6, v61, v3
	v_sub_f32_e32 v7, v60, v3
	v_sub_f32_e32 v10, v59, v3
	v_sub_f32_e32 v11, v58, v3
	v_exp_f32_e32 v58, v11
	v_exp_f32_e32 v59, v10
	v_exp_f32_e32 v60, v7
	v_exp_f32_e32 v61, v6
	v_sub_f32_e32 v7, v57, v3
	v_sub_f32_e32 v56, v56, v3
	v_sub_f32_e32 v11, v55, v3
	v_sub_f32_e32 v10, v54, v3
	v_exp_f32_e32 v10, v10
	v_exp_f32_e32 v11, v11
	v_exp_f32_e32 v54, v56
	v_exp_f32_e32 v55, v7
	v_add_f32_e32 v4, v62, v63
	v_add_f32_e32 v5, v64, v65
	v_sub_f32_e32 v7, v53, v3
	v_sub_f32_e32 v52, v52, v3
	v_sub_f32_e32 v51, v51, v3
	v_sub_f32_e32 v3, v50, v3
	v_add_f32_e32 v4, v4, v5
	v_add_f32_e32 v5, v58, v59
	v_add_f32_e32 v6, v60, v61
	v_exp_f32_e32 v50, v3
	v_exp_f32_e32 v51, v51
	v_exp_f32_e32 v52, v52
	v_exp_f32_e32 v53, v7
	v_add_f32_e32 v4, 0, v4
	v_add_f32_e32 v5, v5, v6
	v_add_f32_e32 v4, v5, v4
	v_add_f32_e32 v5, v10, v11
	v_add_f32_e32 v6, v54, v55
	v_add_f32_e32 v3, v5, v6
	v_add_f32_e32 v3, v3, v4
	v_add_f32_e32 v4, v50, v51
	v_add_f32_e32 v5, v52, v53
	v_add_f32_e32 v4, v4, v5
	v_add_f32_e32 v3, v4, v3
	ds_swizzle_b32 v4, v3 offset:swizzle(SWAP,16)
	s_waitcnt lgkmcnt(0)
	v_add_f32_e32 v3, v3, v4
	v_mov_b32_e32 v4, v3
	s_nop 1
	v_permlane32_swap_b32_e32 v3, v4
	s_and_saveexec_b64 s[6:7], s[2:3]
	v_add_f32_e32 v3, v3, v4
	ds_write_b32 v146, v3 offset:2048
	s_or_b64 exec, exec, s[6:7]
	ds_read_b128 v[4:7], v2 offset:2304
	s_waitcnt lgkmcnt(0)
	v_max_f32_e32 v3, v7, v7
	v_max_f32_e32 v6, v6, v6
	v_max_f32_e32 v3, v6, v3
	v_max3_f32 v3, v4, v5, v3
	v_sub_f32_e32 v4, v49, v3
	v_sub_f32_e32 v5, v48, v3
	v_sub_f32_e32 v6, v47, v3
	v_sub_f32_e32 v7, v46, v3
	v_exp_f32_e32 v46, v7
	v_exp_f32_e32 v47, v6
	v_exp_f32_e32 v48, v5
	v_exp_f32_e32 v49, v4
	v_sub_f32_e32 v6, v45, v3
	v_sub_f32_e32 v7, v44, v3
	v_sub_f32_e32 v43, v43, v3
	v_sub_f32_e32 v42, v42, v3
	v_exp_f32_e32 v42, v42
	v_exp_f32_e32 v43, v43
	v_exp_f32_e32 v56, v7
	v_exp_f32_e32 v57, v6
	v_sub_f32_e32 v41, v41, v3
	v_sub_f32_e32 v40, v40, v3
	v_sub_f32_e32 v7, v39, v3
	v_sub_f32_e32 v6, v38, v3
	v_exp_f32_e32 v6, v6
	v_exp_f32_e32 v7, v7
	v_exp_f32_e32 v38, v40
	v_exp_f32_e32 v39, v41
	v_add_f32_e32 v4, v46, v47
	v_add_f32_e32 v5, v48, v49
	v_sub_f32_e32 v37, v37, v3
	v_sub_f32_e32 v36, v36, v3
	v_sub_f32_e32 v35, v35, v3
	v_sub_f32_e32 v3, v34, v3
	v_add_f32_e32 v4, v4, v5
	v_add_f32_e32 v5, v42, v43
	v_add_f32_e32 v44, v56, v57
	v_exp_f32_e32 v34, v3
	v_exp_f32_e32 v35, v35
	v_exp_f32_e32 v36, v36
	v_exp_f32_e32 v37, v37
	v_add_f32_e32 v4, 0, v4
	v_add_f32_e32 v5, v5, v44
	v_add_f32_e32 v4, v5, v4
	v_add_f32_e32 v5, v6, v7
	v_add_f32_e32 v40, v38, v39
	v_add_f32_e32 v3, v5, v40
	v_add_f32_e32 v3, v3, v4
	v_add_f32_e32 v4, v34, v35
	v_add_f32_e32 v5, v36, v37
	v_add_f32_e32 v4, v4, v5
	v_add_f32_e32 v3, v4, v3
	ds_swizzle_b32 v4, v3 offset:swizzle(SWAP,16)
	s_waitcnt lgkmcnt(0)
	v_add_f32_e32 v3, v3, v4
	v_mov_b32_e32 v4, v3
	s_nop 1
	v_permlane32_swap_b32_e32 v3, v4
	s_and_saveexec_b64 s[6:7], s[2:3]
	v_add_f32_e32 v3, v3, v4
	ds_write_b32 v146, v3 offset:2304
	s_or_b64 exec, exec, s[6:7]
	ds_read_b128 v[148:151], v2 offset:2560
	s_waitcnt lgkmcnt(0)
	v_max_f32_e32 v3, v151, v151
	v_max_f32_e32 v4, v150, v150
	v_max_f32_e32 v3, v4, v3
	v_max3_f32 v3, v148, v149, v3
	v_sub_f32_e32 v4, v33, v3
	v_sub_f32_e32 v5, v32, v3
	v_sub_f32_e32 v31, v31, v3
	v_sub_f32_e32 v30, v30, v3
	v_exp_f32_e32 v30, v30
	v_exp_f32_e32 v31, v31
	v_exp_f32_e32 v32, v5
	v_exp_f32_e32 v33, v4
	v_sub_f32_e32 v40, v29, v3
	v_sub_f32_e32 v41, v28, v3
	v_sub_f32_e32 v27, v27, v3
	v_sub_f32_e32 v26, v26, v3
	v_exp_f32_e32 v28, v26
	v_exp_f32_e32 v29, v27
	v_exp_f32_e32 v44, v41
	v_exp_f32_e32 v45, v40
	v_add_f32_e32 v4, v30, v31
	v_add_f32_e32 v5, v32, v33
	v_add_f32_e32 v4, v4, v5
	v_add_f32_e32 v26, 0, v4
	v_add_f32_e32 v27, v28, v29
	v_add_f32_e32 v40, v44, v45
	v_sub_f32_e32 v25, v25, v3
	v_sub_f32_e32 v24, v24, v3
	v_sub_f32_e32 v5, v23, v3
	v_sub_f32_e32 v4, v22, v3
	v_exp_f32_e32 v4, v4
	v_exp_f32_e32 v5, v5
	v_exp_f32_e32 v22, v24
	v_exp_f32_e32 v23, v25
	v_add_f32_e32 v24, v27, v40
	v_sub_f32_e32 v21, v21, v3
	v_sub_f32_e32 v20, v20, v3
	v_sub_f32_e32 v19, v19, v3
	v_sub_f32_e32 v3, v18, v3
	v_add_f32_e32 v24, v24, v26
	v_exp_f32_e32 v18, v3
	v_exp_f32_e32 v19, v19
	v_exp_f32_e32 v26, v20
	v_exp_f32_e32 v27, v21
	v_add_f32_e32 v25, v4, v5
	v_add_f32_e32 v40, v22, v23
	v_add_f32_e32 v3, v25, v40
	v_add_f32_e32 v20, v18, v19
	v_add_f32_e32 v21, v26, v27
	v_add_f32_e32 v3, v3, v24
	v_add_f32_e32 v20, v20, v21
	v_add_f32_e32 v3, v20, v3
	ds_swizzle_b32 v20, v3 offset:swizzle(SWAP,16)
	s_waitcnt lgkmcnt(0)
	v_add_f32_e32 v3, v3, v20
	v_mov_b32_e32 v20, v3
	s_nop 1
	v_permlane32_swap_b32_e32 v3, v20
	s_and_saveexec_b64 s[6:7], s[2:3]
	v_add_f32_e32 v3, v3, v20
	ds_write_b32 v146, v3 offset:2560
	s_or_b64 exec, exec, s[6:7]
	ds_read_b128 v[148:151], v2 offset:2816
	s_waitcnt lgkmcnt(0)
	v_max_f32_e32 v2, v151, v151
	v_max_f32_e32 v3, v150, v150
	v_max_f32_e32 v2, v3, v2
	v_max3_f32 v147, v148, v149, v2
	v_sub_f32_e32 v2, v17, v147
	v_sub_f32_e32 v3, v16, v147
	v_sub_f32_e32 v15, v15, v147
	v_sub_f32_e32 v14, v14, v147
	v_exp_f32_e32 v14, v14
	v_exp_f32_e32 v15, v15
	v_exp_f32_e32 v20, v3
	v_exp_f32_e32 v21, v2
	v_sub_f32_e32 v16, v133, v147
	v_sub_f32_e32 v17, v132, v147
	v_sub_f32_e32 v13, v13, v147
	v_sub_f32_e32 v12, v12, v147
	v_exp_f32_e32 v24, v12
	v_exp_f32_e32 v25, v13
	v_exp_f32_e32 v40, v17
	v_exp_f32_e32 v41, v16
	v_add_f32_e32 v2, v14, v15
	v_add_f32_e32 v3, v20, v21
	v_add_f32_e32 v2, v2, v3
	v_add_f32_e32 v12, 0, v2
	v_add_f32_e32 v13, v24, v25
	v_add_f32_e32 v16, v40, v41
	v_sub_f32_e32 v17, v137, v147
	v_sub_f32_e32 v132, v136, v147
	v_sub_f32_e32 v3, v9, v147
	v_sub_f32_e32 v2, v8, v147
	v_exp_f32_e32 v2, v2
	v_exp_f32_e32 v3, v3
	v_exp_f32_e32 v8, v132
	v_exp_f32_e32 v9, v17
	v_add_f32_e32 v13, v13, v16
	v_add_f32_e32 v132, v13, v12
	v_sub_f32_e32 v17, v139, v147
	v_sub_f32_e32 v16, v138, v147
	v_sub_f32_e32 v13, v135, v147
	v_sub_f32_e32 v12, v134, v147
	v_exp_f32_e32 v12, v12
	v_exp_f32_e32 v13, v13
	v_exp_f32_e32 v16, v16
	v_exp_f32_e32 v17, v17
	v_add_f32_e32 v133, v2, v3
	v_add_f32_e32 v136, v8, v9
	v_add_f32_e32 v133, v133, v136
	v_add_f32_e32 v132, v133, v132
	v_add_f32_e32 v133, v12, v13
	v_add_f32_e32 v134, v16, v17
	v_add_f32_e32 v133, v133, v134
	v_add_f32_e32 v132, v133, v132
	ds_swizzle_b32 v133, v132 offset:swizzle(SWAP,16)
	s_waitcnt lgkmcnt(0)
	v_add_f32_e32 v132, v132, v133
	v_mov_b32_e32 v133, v132
	s_nop 1
	v_permlane32_swap_b32_e32 v132, v133
	s_and_saveexec_b64 s[6:7], s[2:3]
	v_add_f32_e32 v132, v132, v133
	ds_write_b32 v146, v132 offset:2816
	s_or_b64 exec, exec, s[6:7]
	s_lshl_b32 s2, s16, 5
	s_or_b32 s3, s15, s2
	s_mul_i32 s6, s14, 0x180000
	s_mul_hi_i32 s2, s14, 0x180000
	s_add_u32 s4, s4, s6
	s_addc_u32 s5, s5, s2
	s_add_i32 s2, 0, 0x21000
	s_waitcnt lgkmcnt(0)
	s_barrier
	v_lshl_add_u32 v132, v130, 4, s2
	ds_read_b128 v[132:135], v132
	v_lshl_add_u32 v136, v131, 3, s3
	v_ashrrev_i32_e32 v131, 31, v130
	v_lshlrev_b64 v[130:131], 11, v[130:131]
	v_lshl_add_u64 v[130:131], s[4:5], 0, v[130:131]
	s_waitcnt lgkmcnt(0)
	v_mov_b32_e32 v138, v133
	v_mov_b32_e32 v139, v134
	v_mov_b32_e32 v133, v135
	v_pk_add_f32 v[132:133], v[138:139], v[132:133]
	v_ashrrev_i32_e32 v137, 31, v136
	v_add_f32_e32 v132, v132, v133
	v_rcp_f32_e32 v132, v132
	v_lshl_add_u64 v[130:131], v[136:137], 1, v[130:131]
	s_mov_b32 s3, 0x9800000
	s_mov_b64 s[4:5], 0x9800000
	v_pk_mul_f32 v[126:127], v[126:127], v[132:133] op_sel_hi:[1,0]
	v_pk_mul_f32 v[134:135], v[124:125], v[132:133] op_sel_hi:[1,0]
	v_pk_mul_f32 v[124:125], v[122:123], v[132:133] op_sel_hi:[1,0]
	v_cvt_pk_bf16_f32 v122, v126, v127
	v_add_co_u32_e32 v126, vcc, s3, v130
	v_pk_mul_f32 v[128:129], v[128:129], v[132:133] op_sel_hi:[1,0]
	s_nop 0
	v_addc_co_u32_e32 v127, vcc, 0, v131, vcc
	v_cvt_pk_bf16_f32 v123, v128, v129
	v_pk_mul_f32 v[118:119], v[118:119], v[132:133] op_sel_hi:[1,0]
	v_cvt_pk_bf16_f32 v124, v124, v125
	v_cvt_pk_bf16_f32 v125, v134, v135
	global_store_dwordx4 v[126:127], v[122:125], off
	v_pk_mul_f32 v[120:121], v[120:121], v[132:133] op_sel_hi:[1,0]
	s_mov_b32 s3, 0x9808000
	v_pk_mul_f32 v[122:123], v[116:117], v[132:133] op_sel_hi:[1,0]
	v_pk_mul_f32 v[116:117], v[114:115], v[132:133] op_sel_hi:[1,0]
	v_cvt_pk_bf16_f32 v114, v118, v119
	v_lshl_add_u32 v118, v140, 4, s2
	v_cvt_pk_bf16_f32 v115, v120, v121
	v_cvt_pk_bf16_f32 v116, v116, v117
	v_cvt_pk_bf16_f32 v117, v122, v123
	ds_read_b128 v[118:121], v118
	v_lshl_add_u32 v0, v0, 4, s2
	s_waitcnt lgkmcnt(0)
	v_mov_b32_e32 v122, v119
	v_mov_b32_e32 v123, v120
	v_mov_b32_e32 v119, v121
	v_pk_add_f32 v[118:119], v[122:123], v[118:119]
	v_lshl_add_u64 v[120:121], v[130:131], 0, s[4:5]
	v_add_f32_e32 v118, v118, v119
	v_rcp_f32_e32 v118, v118
	global_store_dwordx4 v[120:121], v[114:117], off offset:256
	v_pk_mul_f32 v[110:111], v[110:111], v[118:119] op_sel_hi:[1,0]
	s_nop 0
	v_pk_mul_f32 v[114:115], v[108:109], v[118:119] op_sel_hi:[1,0]
	v_pk_mul_f32 v[108:109], v[106:107], v[118:119] op_sel_hi:[1,0]
	v_cvt_pk_bf16_f32 v106, v110, v111
	v_add_co_u32_e32 v110, vcc, s3, v130
	v_pk_mul_f32 v[112:113], v[112:113], v[118:119] op_sel_hi:[1,0]
	s_nop 0
	v_addc_co_u32_e32 v111, vcc, 0, v131, vcc
	v_cvt_pk_bf16_f32 v107, v112, v113
	v_pk_mul_f32 v[102:103], v[102:103], v[118:119] op_sel_hi:[1,0]
	v_cvt_pk_bf16_f32 v108, v108, v109
	v_cvt_pk_bf16_f32 v109, v114, v115
	global_store_dwordx4 v[110:111], v[106:109], off
	v_pk_mul_f32 v[104:105], v[104:105], v[118:119] op_sel_hi:[1,0]
	s_mov_b32 s3, 0x9810000
	v_pk_mul_f32 v[106:107], v[100:101], v[118:119] op_sel_hi:[1,0]
	v_pk_mul_f32 v[100:101], v[98:99], v[118:119] op_sel_hi:[1,0]
	v_cvt_pk_bf16_f32 v98, v102, v103
	v_lshl_add_u32 v102, v141, 4, s2
	v_cvt_pk_bf16_f32 v99, v104, v105
	v_cvt_pk_bf16_f32 v100, v100, v101
	v_cvt_pk_bf16_f32 v101, v106, v107
	ds_read_b128 v[102:105], v102
	global_store_dwordx4 v[110:111], v[98:101], off offset:256
	s_waitcnt lgkmcnt(0)
	v_mov_b32_e32 v106, v103
	v_mov_b32_e32 v107, v104
	v_mov_b32_e32 v103, v105
	v_pk_add_f32 v[102:103], v[106:107], v[102:103]
	s_nop 0
	v_add_f32_e32 v102, v102, v103
	v_rcp_f32_e32 v102, v102
	s_nop 0
	v_pk_mul_f32 v[94:95], v[94:95], v[102:103] op_sel_hi:[1,0]
	v_pk_mul_f32 v[98:99], v[92:93], v[102:103] op_sel_hi:[1,0]
	v_pk_mul_f32 v[92:93], v[90:91], v[102:103] op_sel_hi:[1,0]
	v_cvt_pk_bf16_f32 v90, v94, v95
	v_add_co_u32_e32 v94, vcc, s3, v130
	v_pk_mul_f32 v[96:97], v[96:97], v[102:103] op_sel_hi:[1,0]
	s_nop 0
	v_addc_co_u32_e32 v95, vcc, 0, v131, vcc
	v_cvt_pk_bf16_f32 v91, v96, v97
	v_pk_mul_f32 v[86:87], v[86:87], v[102:103] op_sel_hi:[1,0]
	v_cvt_pk_bf16_f32 v92, v92, v93
	v_cvt_pk_bf16_f32 v93, v98, v99
	global_store_dwordx4 v[94:95], v[90:93], off
	v_pk_mul_f32 v[88:89], v[88:89], v[102:103] op_sel_hi:[1,0]
	s_mov_b32 s3, 0x9818000
	v_pk_mul_f32 v[90:91], v[84:85], v[102:103] op_sel_hi:[1,0]
	v_pk_mul_f32 v[84:85], v[82:83], v[102:103] op_sel_hi:[1,0]
	v_cvt_pk_bf16_f32 v82, v86, v87
	v_lshl_add_u32 v86, v142, 4, s2
	v_cvt_pk_bf16_f32 v83, v88, v89
	v_cvt_pk_bf16_f32 v84, v84, v85
	v_cvt_pk_bf16_f32 v85, v90, v91
	ds_read_b128 v[86:89], v86
	global_store_dwordx4 v[94:95], v[82:85], off offset:256
	s_waitcnt lgkmcnt(0)
	v_mov_b32_e32 v90, v87
	v_mov_b32_e32 v91, v88
	v_mov_b32_e32 v87, v89
	v_pk_add_f32 v[86:87], v[90:91], v[86:87]
	s_nop 0
	v_add_f32_e32 v86, v86, v87
	v_rcp_f32_e32 v86, v86
	s_nop 0
	v_pk_mul_f32 v[78:79], v[78:79], v[86:87] op_sel_hi:[1,0]
	v_pk_mul_f32 v[82:83], v[76:77], v[86:87] op_sel_hi:[1,0]
	v_pk_mul_f32 v[76:77], v[74:75], v[86:87] op_sel_hi:[1,0]
	v_cvt_pk_bf16_f32 v74, v78, v79
	v_add_co_u32_e32 v78, vcc, s3, v130
	v_pk_mul_f32 v[80:81], v[80:81], v[86:87] op_sel_hi:[1,0]
	s_nop 0
	v_addc_co_u32_e32 v79, vcc, 0, v131, vcc
	v_cvt_pk_bf16_f32 v75, v80, v81
	v_cvt_pk_bf16_f32 v76, v76, v77
	v_cvt_pk_bf16_f32 v77, v82, v83
	global_store_dwordx4 v[78:79], v[74:77], off
	v_pk_mul_f32 v[72:73], v[72:73], v[86:87] op_sel_hi:[1,0]
	v_pk_mul_f32 v[70:71], v[70:71], v[86:87] op_sel_hi:[1,0]
	v_pk_mul_f32 v[74:75], v[68:69], v[86:87] op_sel_hi:[1,0]
	v_pk_mul_f32 v[68:69], v[66:67], v[86:87] op_sel_hi:[1,0]
	v_cvt_pk_bf16_f32 v66, v70, v71
	v_cvt_pk_bf16_f32 v67, v72, v73
	s_mov_b32 s3, 0x9840000
	v_cvt_pk_bf16_f32 v68, v68, v69
	v_cvt_pk_bf16_f32 v69, v74, v75
	ds_read_b128 v[70:73], v0
	global_store_dwordx4 v[78:79], v[66:69], off offset:256
	s_waitcnt lgkmcnt(0)
	v_mov_b32_e32 v74, v71
	v_mov_b32_e32 v75, v72
	v_mov_b32_e32 v71, v73
	v_pk_add_f32 v[70:71], v[74:75], v[70:71]
	s_nop 0
	v_add_f32_e32 v0, v70, v71
	v_rcp_f32_e32 v0, v0
	s_nop 0
	v_pk_mul_f32 v[62:63], v[62:63], v[0:1] op_sel_hi:[1,0]
	v_pk_mul_f32 v[66:67], v[60:61], v[0:1] op_sel_hi:[1,0]
	v_pk_mul_f32 v[60:61], v[58:59], v[0:1] op_sel_hi:[1,0]
	v_cvt_pk_bf16_f32 v58, v62, v63
	v_add_co_u32_e32 v62, vcc, s3, v130
	v_pk_mul_f32 v[64:65], v[64:65], v[0:1] op_sel_hi:[1,0]
	s_nop 0
	v_addc_co_u32_e32 v63, vcc, 0, v131, vcc
	v_cvt_pk_bf16_f32 v59, v64, v65
	v_cvt_pk_bf16_f32 v60, v60, v61
	v_cvt_pk_bf16_f32 v61, v66, v67
	global_store_dwordx4 v[62:63], v[58:61], off
	v_pk_mul_f32 v[54:55], v[54:55], v[0:1] op_sel_hi:[1,0]
	v_pk_mul_f32 v[10:11], v[10:11], v[0:1] op_sel_hi:[1,0]
	v_pk_mul_f32 v[58:59], v[52:53], v[0:1] op_sel_hi:[1,0]
	v_pk_mul_f32 v[52:53], v[50:51], v[0:1] op_sel_hi:[1,0]
	v_lshl_add_u32 v0, v143, 4, s2
	v_cvt_pk_bf16_f32 v50, v10, v11
	v_cvt_pk_bf16_f32 v51, v54, v55
	v_cvt_pk_bf16_f32 v52, v52, v53
	v_cvt_pk_bf16_f32 v53, v58, v59
	ds_read_b128 v[58:61], v0
	s_mov_b32 s3, 0x9848000
	global_store_dwordx4 v[62:63], v[50:53], off offset:256
	s_waitcnt lgkmcnt(0)
	v_mov_b32_e32 v10, v59
	v_mov_b32_e32 v11, v60
	v_mov_b32_e32 v59, v61
	v_pk_add_f32 v[10:11], v[10:11], v[58:59]
	s_nop 0
	v_add_f32_e32 v0, v10, v11
	v_rcp_f32_e32 v0, v0
	s_nop 0
	v_pk_mul_f32 v[10:11], v[48:49], v[0:1] op_sel_hi:[1,0]
	v_pk_mul_f32 v[46:47], v[46:47], v[0:1] op_sel_hi:[1,0]
	v_pk_mul_f32 v[42:43], v[42:43], v[0:1] op_sel_hi:[1,0]
	v_cvt_pk_bf16_f32 v46, v46, v47
	v_cvt_pk_bf16_f32 v47, v10, v11
	v_add_co_u32_e32 v10, vcc, s3, v130
	v_pk_mul_f32 v[50:51], v[56:57], v[0:1] op_sel_hi:[1,0]
	v_cvt_pk_bf16_f32 v48, v42, v43
	s_nop 0
	v_addc_co_u32_e32 v11, vcc, 0, v131, vcc
	v_cvt_pk_bf16_f32 v49, v50, v51
	v_pk_mul_f32 v[38:39], v[38:39], v[0:1] op_sel_hi:[1,0]
	v_pk_mul_f32 v[6:7], v[6:7], v[0:1] op_sel_hi:[1,0]
	v_pk_mul_f32 v[42:43], v[36:37], v[0:1] op_sel_hi:[1,0]
	v_pk_mul_f32 v[36:37], v[34:35], v[0:1] op_sel_hi:[1,0]
	v_lshl_add_u32 v0, v144, 4, s2
	global_store_dwordx4 v[10:11], v[46:49], off
	v_cvt_pk_bf16_f32 v34, v6, v7
	v_cvt_pk_bf16_f32 v35, v38, v39
	v_cvt_pk_bf16_f32 v36, v36, v37
	v_cvt_pk_bf16_f32 v37, v42, v43
	ds_read_b128 v[46:49], v0
	global_store_dwordx4 v[10:11], v[34:37], off offset:256
	s_mov_b32 s3, 0x9850000
	s_waitcnt lgkmcnt(0)
	v_mov_b32_e32 v6, v47
	v_mov_b32_e32 v7, v48
	v_mov_b32_e32 v47, v49
	v_pk_add_f32 v[6:7], v[6:7], v[46:47]
	s_nop 0
	v_add_f32_e32 v0, v6, v7
	v_rcp_f32_e32 v0, v0
	s_nop 0
	v_pk_mul_f32 v[10:11], v[30:31], v[0:1] op_sel_hi:[1,0]
	v_pk_mul_f32 v[6:7], v[32:33], v[0:1] op_sel_hi:[1,0]
	v_pk_mul_f32 v[30:31], v[28:29], v[0:1] op_sel_hi:[1,0]
	v_cvt_pk_bf16_f32 v28, v10, v11
	v_add_co_u32_e32 v10, vcc, s3, v130
	v_pk_mul_f32 v[32:33], v[44:45], v[0:1] op_sel_hi:[1,0]
	v_cvt_pk_bf16_f32 v29, v6, v7
	s_nop 0
	v_addc_co_u32_e32 v11, vcc, 0, v131, vcc
	v_pk_mul_f32 v[6:7], v[22:23], v[0:1] op_sel_hi:[1,0]
	v_pk_mul_f32 v[4:5], v[4:5], v[0:1] op_sel_hi:[1,0]
	v_pk_mul_f32 v[22:23], v[26:27], v[0:1] op_sel_hi:[1,0]
	v_pk_mul_f32 v[18:19], v[18:19], v[0:1] op_sel_hi:[1,0]
	v_lshl_add_u32 v0, v145, 4, s2
	v_cvt_pk_bf16_f32 v30, v30, v31
	v_cvt_pk_bf16_f32 v31, v32, v33
	global_store_dwordx4 v[10:11], v[28:31], off
	v_cvt_pk_bf16_f32 v4, v4, v5
	v_cvt_pk_bf16_f32 v5, v6, v7
	v_cvt_pk_bf16_f32 v6, v18, v19
	v_cvt_pk_bf16_f32 v7, v22, v23
	ds_read_b128 v[26:29], v0
	global_store_dwordx4 v[10:11], v[4:7], off offset:256
	s_mov_b32 s2, 0x9858000
	s_waitcnt lgkmcnt(0)
	v_mov_b32_e32 v18, v27
	v_mov_b32_e32 v19, v28
	v_mov_b32_e32 v27, v29
	v_pk_add_f32 v[18:19], v[18:19], v[26:27]
	s_nop 0
	v_add_f32_e32 v0, v18, v19
	v_rcp_f32_e32 v0, v0
	s_nop 0
	v_pk_mul_f32 v[6:7], v[20:21], v[0:1] op_sel_hi:[1,0]
	v_pk_mul_f32 v[4:5], v[14:15], v[0:1] op_sel_hi:[1,0]
	v_pk_mul_f32 v[10:11], v[40:41], v[0:1] op_sel_hi:[1,0]
	v_pk_mul_f32 v[14:15], v[24:25], v[0:1] op_sel_hi:[1,0]
	v_cvt_pk_bf16_f32 v4, v4, v5
	v_cvt_pk_bf16_f32 v5, v6, v7
	v_pk_mul_f32 v[2:3], v[2:3], v[0:1] op_sel_hi:[1,0]
	v_cvt_pk_bf16_f32 v6, v14, v15
	v_cvt_pk_bf16_f32 v7, v10, v11
	v_add_co_u32_e32 v10, vcc, s2, v130
	s_nop 1
	v_addc_co_u32_e32 v11, vcc, 0, v131, vcc
	global_store_dwordx4 v[10:11], v[4:7], off
	v_cvt_pk_bf16_f32 v2, v2, v3
	s_nop 1
	v_pk_mul_f32 v[4:5], v[8:9], v[0:1] op_sel_hi:[1,0]
	v_pk_mul_f32 v[6:7], v[16:17], v[0:1] op_sel_hi:[1,0]
	v_pk_mul_f32 v[8:9], v[12:13], v[0:1] op_sel_hi:[1,0]
	v_cvt_pk_bf16_f32 v3, v4, v5
	s_nop 0
	v_cvt_pk_bf16_f32 v4, v8, v9
	v_cvt_pk_bf16_f32 v5, v6, v7
	global_store_dwordx4 v[10:11], v[2:5], off offset:256
